# v19 with 54 of the remaining DPP pads shrunk from two wait states to one where one suffices
# baseline (speedup 1.0000x reference)
.LBB0_390:
	s_or_b64 exec, exec, s[8:9]
	s_waitcnt lgkmcnt(0)
	s_barrier
	v_add_u32_e32 v187, s5, v189
	ds_read_b128 v[148:151], v187 offset:9216
	ds_read_b128 v[152:155], v187 offset:8192
	ds_read_b128 v[40:43], v187 offset:10240
	ds_read_b128 v[160:163], v187 offset:11264
	s_add_i32 s4, s5, s81
	s_add_i32 s12, s4, 0xfffffc00
	v_cmp_eq_u32_e64 s[8:9], 0, v210
	v_cmp_gt_u32_e64 s[10:11], 2, v210
	s_waitcnt lgkmcnt(0)
	v_pk_fma_f32 v[6:7], v[166:167], v[42:43], v[162:163]
	v_pk_fma_f32 v[4:5], v[164:165], v[40:41], v[160:161]
	v_add_u32_e32 v191, s12, v189
	s_add_i32 s12, s4, 0xfffff800
	v_fmac_f32_dpp v4, v164, v148 row_shr:1 row_mask:0xf bank_mask:0xf bound_ctrl:1
	v_fmac_f32_dpp v5, v165, v149 row_shr:1 row_mask:0xf bank_mask:0xf bound_ctrl:1
	v_fmac_f32_dpp v4, v164, v152 row_shr:2 row_mask:0xf bank_mask:0xf bound_ctrl:1
	v_fmac_f32_dpp v5, v165, v153 row_shr:2 row_mask:0xf bank_mask:0xf bound_ctrl:1
	v_fmac_f32_dpp v6, v166, v150 row_shr:1 row_mask:0xf bank_mask:0xf bound_ctrl:1
	v_fmac_f32_dpp v7, v167, v151 row_shr:1 row_mask:0xf bank_mask:0xf bound_ctrl:1
	v_fmac_f32_dpp v6, v166, v154 row_shr:2 row_mask:0xf bank_mask:0xf bound_ctrl:1
	v_fmac_f32_dpp v7, v167, v155 row_shr:2 row_mask:0xf bank_mask:0xf bound_ctrl:1
	v_cndmask_b32_e64 v195, 0, v148, s[8:9]
	v_cndmask_b32_e64 v211, 0, v152, s[10:11]
	v_cndmask_b32_e64 v201, 0, v149, s[8:9]
	v_cndmask_b32_e64 v213, 0, v153, s[10:11]
	v_cndmask_b32_e64 v199, 0, v150, s[8:9]
	v_cndmask_b32_e64 v212, 0, v154, s[10:11]
	v_cndmask_b32_e64 v197, 0, v151, s[8:9]
	v_cndmask_b32_e64 v210, 0, v155, s[10:11]
	v_add_u32_e32 v193, s12, v189
	v_fmac_f32_dpp v4, v156, v195 row_ror:1 row_mask:0xf bank_mask:0xf
	v_fmac_f32_dpp v5, v157, v201 row_ror:1 row_mask:0xf bank_mask:0xf
	v_fmac_f32_dpp v4, v156, v211 row_ror:2 row_mask:0xf bank_mask:0xf
	v_fmac_f32_dpp v5, v157, v213 row_ror:2 row_mask:0xf bank_mask:0xf
	v_fmac_f32_dpp v6, v158, v199 row_ror:1 row_mask:0xf bank_mask:0xf
	v_fmac_f32_dpp v7, v159, v197 row_ror:1 row_mask:0xf bank_mask:0xf
	v_fmac_f32_dpp v6, v158, v212 row_ror:2 row_mask:0xf bank_mask:0xf
	v_fmac_f32_dpp v7, v159, v210 row_ror:2 row_mask:0xf bank_mask:0xf
	s_nop 0
	v_pk_fma_f32 v[18:19], v[158:159], v[42:43], v[162:163]
	v_pk_fma_f32 v[16:17], v[156:157], v[40:41], v[160:161]
	v_mov_b32_e32 v1, v19
	v_mov_b32_e32 v0, v17
	s_nop 0
	v_fmac_f32_dpp v16, v156, v148 row_shr:1 row_mask:0xf bank_mask:0xf bound_ctrl:1
	v_fmac_f32_dpp v0, v157, v149 row_shr:1 row_mask:0xf bank_mask:0xf bound_ctrl:1
	v_fmac_f32_dpp v16, v156, v152 row_shr:2 row_mask:0xf bank_mask:0xf bound_ctrl:1
	v_fmac_f32_dpp v0, v157, v153 row_shr:2 row_mask:0xf bank_mask:0xf bound_ctrl:1
	v_fmac_f32_dpp v18, v158, v150 row_shr:1 row_mask:0xf bank_mask:0xf bound_ctrl:1
	v_fmac_f32_dpp v1, v159, v151 row_shr:1 row_mask:0xf bank_mask:0xf bound_ctrl:1
	v_fmac_f32_dpp v18, v158, v154 row_shr:2 row_mask:0xf bank_mask:0xf bound_ctrl:1
	v_fmac_f32_dpp v1, v159, v155 row_shr:2 row_mask:0xf bank_mask:0xf bound_ctrl:1
	s_nop 0
	v_fmac_f32_dpp v16, v144, v195 row_ror:1 row_mask:0xf bank_mask:0xf
	v_fmac_f32_dpp v0, v145, v201 row_ror:1 row_mask:0xf bank_mask:0xf
	v_fmac_f32_dpp v16, v144, v211 row_ror:2 row_mask:0xf bank_mask:0xf
	v_fmac_f32_dpp v0, v145, v213 row_ror:2 row_mask:0xf bank_mask:0xf
	v_fmac_f32_dpp v18, v146, v199 row_ror:1 row_mask:0xf bank_mask:0xf
	v_fmac_f32_dpp v1, v147, v197 row_ror:1 row_mask:0xf bank_mask:0xf
	v_fmac_f32_dpp v18, v146, v212 row_ror:2 row_mask:0xf bank_mask:0xf
	v_fmac_f32_dpp v1, v147, v210 row_ror:2 row_mask:0xf bank_mask:0xf
	s_nop 0
	v_mov_b32_e32 v17, v0
	v_mov_b32_e32 v19, v1
	v_pk_fma_f32 v[34:35], v[146:147], v[42:43], v[162:163]
	v_pk_fma_f32 v[32:33], v[144:145], v[40:41], v[160:161]
	v_mov_b32_e32 v0, v35
	s_nop 0
	v_fmac_f32_dpp v32, v144, v148 row_shr:1 row_mask:0xf bank_mask:0xf bound_ctrl:1
	v_fmac_f32_dpp v33, v145, v149 row_shr:1 row_mask:0xf bank_mask:0xf bound_ctrl:1
	v_fmac_f32_dpp v32, v144, v152 row_shr:2 row_mask:0xf bank_mask:0xf bound_ctrl:1
	v_fmac_f32_dpp v33, v145, v153 row_shr:2 row_mask:0xf bank_mask:0xf bound_ctrl:1
	v_fmac_f32_dpp v34, v146, v150 row_shr:1 row_mask:0xf bank_mask:0xf bound_ctrl:1
	v_fmac_f32_dpp v0, v147, v151 row_shr:1 row_mask:0xf bank_mask:0xf bound_ctrl:1
	v_fmac_f32_dpp v34, v146, v154 row_shr:2 row_mask:0xf bank_mask:0xf bound_ctrl:1
	v_fmac_f32_dpp v0, v147, v155 row_shr:2 row_mask:0xf bank_mask:0xf bound_ctrl:1
	s_nop 0
	v_fmac_f32_dpp v32, v140, v195 row_ror:1 row_mask:0xf bank_mask:0xf
	v_fmac_f32_dpp v33, v141, v201 row_ror:1 row_mask:0xf bank_mask:0xf
	v_fmac_f32_dpp v32, v140, v211 row_ror:2 row_mask:0xf bank_mask:0xf
	v_fmac_f32_dpp v33, v141, v213 row_ror:2 row_mask:0xf bank_mask:0xf
	v_fmac_f32_dpp v34, v142, v199 row_ror:1 row_mask:0xf bank_mask:0xf
	v_fmac_f32_dpp v0, v143, v197 row_ror:1 row_mask:0xf bank_mask:0xf
	v_fmac_f32_dpp v34, v142, v212 row_ror:2 row_mask:0xf bank_mask:0xf
	v_fmac_f32_dpp v0, v143, v210 row_ror:2 row_mask:0xf bank_mask:0xf
	s_nop 0
	v_mov_b32_e32 v35, v0
	v_pk_fma_f32 v[0:1], v[142:143], v[42:43], v[162:163]
	v_pk_fma_f32 v[2:3], v[140:141], v[40:41], v[160:161]
	v_mov_b32_e32 v62, v0
	v_mov_b32_e32 v60, v2
	v_cndmask_b32_e64 v0, 0, 1, s[36:37]
	s_nop 0
	v_fmac_f32_dpp v60, v140, v148 row_shr:1 row_mask:0xf bank_mask:0xf bound_ctrl:1
	v_fmac_f32_dpp v3, v141, v149 row_shr:1 row_mask:0xf bank_mask:0xf bound_ctrl:1
	v_fmac_f32_dpp v60, v140, v152 row_shr:2 row_mask:0xf bank_mask:0xf bound_ctrl:1
	v_fmac_f32_dpp v3, v141, v153 row_shr:2 row_mask:0xf bank_mask:0xf bound_ctrl:1
	v_fmac_f32_dpp v62, v142, v150 row_shr:1 row_mask:0xf bank_mask:0xf bound_ctrl:1
	v_fmac_f32_dpp v1, v143, v151 row_shr:1 row_mask:0xf bank_mask:0xf bound_ctrl:1
	v_fmac_f32_dpp v62, v142, v154 row_shr:2 row_mask:0xf bank_mask:0xf bound_ctrl:1
	v_fmac_f32_dpp v1, v143, v155 row_shr:2 row_mask:0xf bank_mask:0xf bound_ctrl:1
	v_cmp_ne_u32_e64 s[12:13], 1, v0
	v_mov_b32_e32 v61, v3
	s_andn2_b64 vcc, exec, s[36:37]
	v_mov_b32_e32 v63, v1
	s_cbranch_vccnz .LBB0_392
	ds_read_b128 v[8:11], v191
	ds_read_b128 v[140:143], v193
	s_waitcnt lgkmcnt(0)
	v_cndmask_b32_e64 v0, v8, v140, s[8:9]
	v_mul_f32_e32 v0, v211, v0
	v_fmac_f32_e32 v0, v195, v8
	v_add_f32_e32 v60, v60, v0
	v_cndmask_b32_e64 v0, v10, v142, s[8:9]
	v_mul_f32_e32 v0, v212, v0
	v_fmac_f32_e32 v0, v199, v10
	v_cndmask_b32_e64 v2, v9, v141, s[8:9]
	v_add_f32_e32 v62, v62, v0
	v_cndmask_b32_e64 v0, v11, v143, s[8:9]
	v_mul_f32_e32 v2, v213, v2
	v_mul_f32_e32 v0, v210, v0
	v_fmac_f32_e32 v2, v201, v9
	v_fmac_f32_e32 v0, v197, v11
	v_add_f32_e32 v61, v3, v2
	v_add_f32_e32 v63, v1, v0
.LBB0_392:
	s_add_i32 s5, s5, s82
	s_add_i32 s14, s5, 0xfffffc00
	v_pk_fma_f32 v[2:3], v[22:23], v[42:43], v[162:163]
	v_pk_fma_f32 v[0:1], v[20:21], v[40:41], v[160:161]
	v_add_u32_e32 v156, s14, v189
	s_add_i32 s14, s5, 0xfffff800
	v_fmac_f32_dpp v0, v20, v148 row_shr:1 row_mask:0xf bank_mask:0xf bound_ctrl:1
	v_fmac_f32_dpp v1, v21, v149 row_shr:1 row_mask:0xf bank_mask:0xf bound_ctrl:1
	v_fmac_f32_dpp v0, v20, v152 row_shr:2 row_mask:0xf bank_mask:0xf bound_ctrl:1
	v_fmac_f32_dpp v1, v21, v153 row_shr:2 row_mask:0xf bank_mask:0xf bound_ctrl:1
	v_fmac_f32_dpp v2, v22, v150 row_shr:1 row_mask:0xf bank_mask:0xf bound_ctrl:1
	v_fmac_f32_dpp v3, v23, v151 row_shr:1 row_mask:0xf bank_mask:0xf bound_ctrl:1
	v_fmac_f32_dpp v2, v22, v154 row_shr:2 row_mask:0xf bank_mask:0xf bound_ctrl:1
	v_fmac_f32_dpp v3, v23, v155 row_shr:2 row_mask:0xf bank_mask:0xf bound_ctrl:1
	v_add_u32_e32 v157, s14, v189
	v_fmac_f32_dpp v0, v48, v195 row_ror:1 row_mask:0xf bank_mask:0xf
	v_fmac_f32_dpp v1, v49, v201 row_ror:1 row_mask:0xf bank_mask:0xf
	v_fmac_f32_dpp v0, v48, v211 row_ror:2 row_mask:0xf bank_mask:0xf
	v_fmac_f32_dpp v1, v49, v213 row_ror:2 row_mask:0xf bank_mask:0xf
	v_fmac_f32_dpp v2, v50, v199 row_ror:1 row_mask:0xf bank_mask:0xf
	v_fmac_f32_dpp v3, v51, v197 row_ror:1 row_mask:0xf bank_mask:0xf
	v_fmac_f32_dpp v2, v50, v212 row_ror:2 row_mask:0xf bank_mask:0xf
	v_fmac_f32_dpp v3, v51, v210 row_ror:2 row_mask:0xf bank_mask:0xf
	s_nop 0
	v_pk_fma_f32 v[10:11], v[50:51], v[42:43], v[162:163]
	v_pk_fma_f32 v[8:9], v[48:49], v[40:41], v[160:161]
	s_nop 0
	s_nop 0
	v_fmac_f32_dpp v8, v48, v148 row_shr:1 row_mask:0xf bank_mask:0xf bound_ctrl:1
	v_fmac_f32_dpp v9, v49, v149 row_shr:1 row_mask:0xf bank_mask:0xf bound_ctrl:1
	v_fmac_f32_dpp v8, v48, v152 row_shr:2 row_mask:0xf bank_mask:0xf bound_ctrl:1
	v_fmac_f32_dpp v9, v49, v153 row_shr:2 row_mask:0xf bank_mask:0xf bound_ctrl:1
	v_fmac_f32_dpp v10, v50, v150 row_shr:1 row_mask:0xf bank_mask:0xf bound_ctrl:1
	v_fmac_f32_dpp v11, v51, v151 row_shr:1 row_mask:0xf bank_mask:0xf bound_ctrl:1
	v_fmac_f32_dpp v10, v50, v154 row_shr:2 row_mask:0xf bank_mask:0xf bound_ctrl:1
	v_fmac_f32_dpp v11, v51, v155 row_shr:2 row_mask:0xf bank_mask:0xf bound_ctrl:1
	s_nop 0
	v_fmac_f32_dpp v8, v68, v195 row_ror:1 row_mask:0xf bank_mask:0xf
	v_fmac_f32_dpp v9, v69, v201 row_ror:1 row_mask:0xf bank_mask:0xf
	v_fmac_f32_dpp v8, v68, v211 row_ror:2 row_mask:0xf bank_mask:0xf
	v_fmac_f32_dpp v9, v69, v213 row_ror:2 row_mask:0xf bank_mask:0xf
	v_fmac_f32_dpp v10, v70, v199 row_ror:1 row_mask:0xf bank_mask:0xf
	v_fmac_f32_dpp v11, v71, v197 row_ror:1 row_mask:0xf bank_mask:0xf
	v_fmac_f32_dpp v10, v70, v212 row_ror:2 row_mask:0xf bank_mask:0xf
	v_fmac_f32_dpp v11, v71, v210 row_ror:2 row_mask:0xf bank_mask:0xf
	s_nop 0
	v_pk_fma_f32 v[22:23], v[70:71], v[42:43], v[162:163]
	v_pk_fma_f32 v[20:21], v[68:69], v[40:41], v[160:161]
	s_nop 0
	s_nop 0
	v_fmac_f32_dpp v20, v68, v148 row_shr:1 row_mask:0xf bank_mask:0xf bound_ctrl:1
	v_fmac_f32_dpp v21, v69, v149 row_shr:1 row_mask:0xf bank_mask:0xf bound_ctrl:1
	v_fmac_f32_dpp v20, v68, v152 row_shr:2 row_mask:0xf bank_mask:0xf bound_ctrl:1
	v_fmac_f32_dpp v21, v69, v153 row_shr:2 row_mask:0xf bank_mask:0xf bound_ctrl:1
	v_fmac_f32_dpp v22, v70, v150 row_shr:1 row_mask:0xf bank_mask:0xf bound_ctrl:1
	v_fmac_f32_dpp v23, v71, v151 row_shr:1 row_mask:0xf bank_mask:0xf bound_ctrl:1
	v_fmac_f32_dpp v22, v70, v154 row_shr:2 row_mask:0xf bank_mask:0xf bound_ctrl:1
	v_fmac_f32_dpp v23, v71, v155 row_shr:2 row_mask:0xf bank_mask:0xf bound_ctrl:1
	s_nop 0
	v_fmac_f32_dpp v20, v80, v195 row_ror:1 row_mask:0xf bank_mask:0xf
	v_fmac_f32_dpp v21, v81, v201 row_ror:1 row_mask:0xf bank_mask:0xf
	v_fmac_f32_dpp v20, v80, v211 row_ror:2 row_mask:0xf bank_mask:0xf
	v_fmac_f32_dpp v21, v81, v213 row_ror:2 row_mask:0xf bank_mask:0xf
	v_fmac_f32_dpp v22, v82, v199 row_ror:1 row_mask:0xf bank_mask:0xf
	v_fmac_f32_dpp v23, v83, v197 row_ror:1 row_mask:0xf bank_mask:0xf
	v_fmac_f32_dpp v22, v82, v212 row_ror:2 row_mask:0xf bank_mask:0xf
	v_fmac_f32_dpp v23, v83, v210 row_ror:2 row_mask:0xf bank_mask:0xf
	s_nop 0
	v_cndmask_b32_e64 v48, 0, 1, s[38:39]
	v_pk_fma_f32 v[42:43], v[82:83], v[42:43], v[162:163]
	v_pk_fma_f32 v[40:41], v[80:81], v[40:41], v[160:161]
	v_cmp_ne_u32_e64 s[14:15], 1, v48
	s_andn2_b64 vcc, exec, s[38:39]
	s_nop 1
	v_fmac_f32_dpp v40, v80, v148 row_shr:1 row_mask:0xf bank_mask:0xf bound_ctrl:1
	v_fmac_f32_dpp v41, v81, v149 row_shr:1 row_mask:0xf bank_mask:0xf bound_ctrl:1
	v_fmac_f32_dpp v40, v80, v152 row_shr:2 row_mask:0xf bank_mask:0xf bound_ctrl:1
	v_fmac_f32_dpp v41, v81, v153 row_shr:2 row_mask:0xf bank_mask:0xf bound_ctrl:1
	v_fmac_f32_dpp v42, v82, v150 row_shr:1 row_mask:0xf bank_mask:0xf bound_ctrl:1
	v_fmac_f32_dpp v43, v83, v151 row_shr:1 row_mask:0xf bank_mask:0xf bound_ctrl:1
	v_fmac_f32_dpp v42, v82, v154 row_shr:2 row_mask:0xf bank_mask:0xf bound_ctrl:1
	v_fmac_f32_dpp v43, v83, v155 row_shr:2 row_mask:0xf bank_mask:0xf bound_ctrl:1
	s_cbranch_vccnz .LBB0_394
	ds_read_b128 v[48:51], v156
	ds_read_b128 v[68:71], v157
	s_waitcnt lgkmcnt(0)
	v_cndmask_b32_e64 v68, v48, v68, s[8:9]
	v_mul_f32_e32 v68, v211, v68
	v_fmac_f32_e32 v68, v195, v48
	v_cndmask_b32_e64 v48, v50, v70, s[8:9]
	v_mul_f32_e32 v48, v212, v48
	v_fmac_f32_e32 v48, v199, v50
	v_cndmask_b32_e64 v69, v49, v69, s[8:9]
	v_add_f32_e32 v42, v42, v48
	v_cndmask_b32_e64 v48, v51, v71, s[8:9]
	v_mul_f32_e32 v69, v213, v69
	v_mul_f32_e32 v48, v210, v48
	v_fmac_f32_e32 v69, v201, v49
	v_fmac_f32_e32 v48, v197, v51
	v_add_f32_e32 v40, v40, v68
	v_add_f32_e32 v41, v41, v69
	v_add_f32_e32 v43, v43, v48
.LBB0_394:
	ds_read_b128 v[140:143], v187 offset:9232
	ds_read_b128 v[144:147], v187 offset:8208
	ds_read_b128 v[148:151], v187 offset:10256
	ds_read_b128 v[152:155], v187 offset:11280
	s_waitcnt lgkmcnt(3)
	v_cndmask_b32_e64 v159, 0, v140, s[8:9]
	s_waitcnt lgkmcnt(2)
	v_cndmask_b32_e64 v163, 0, v144, s[10:11]
	v_cndmask_b32_e64 v161, 0, v141, s[8:9]
	s_waitcnt lgkmcnt(0)
	v_pk_fma_f32 v[68:69], v[96:97], v[148:149], v[152:153]
	v_pk_fma_f32 v[70:71], v[98:99], v[150:151], v[154:155]
	v_mov_b32_e32 v48, v69
	s_nop 0
	v_fmac_f32_dpp v68, v96, v140 row_shr:1 row_mask:0xf bank_mask:0xf bound_ctrl:1
	v_fmac_f32_dpp v48, v97, v141 row_shr:1 row_mask:0xf bank_mask:0xf bound_ctrl:1
	v_fmac_f32_dpp v68, v96, v144 row_shr:2 row_mask:0xf bank_mask:0xf bound_ctrl:1
	v_fmac_f32_dpp v48, v97, v145 row_shr:2 row_mask:0xf bank_mask:0xf bound_ctrl:1
	v_fmac_f32_dpp v70, v98, v142 row_shr:1 row_mask:0xf bank_mask:0xf bound_ctrl:1
	v_fmac_f32_dpp v71, v99, v143 row_shr:1 row_mask:0xf bank_mask:0xf bound_ctrl:1
	v_fmac_f32_dpp v70, v98, v146 row_shr:2 row_mask:0xf bank_mask:0xf bound_ctrl:1
	v_fmac_f32_dpp v71, v99, v147 row_shr:2 row_mask:0xf bank_mask:0xf bound_ctrl:1
	v_cndmask_b32_e64 v165, 0, v145, s[10:11]
	v_cndmask_b32_e64 v160, 0, v142, s[8:9]
	v_cndmask_b32_e64 v164, 0, v146, s[10:11]
	v_cndmask_b32_e64 v158, 0, v143, s[8:9]
	v_cndmask_b32_e64 v162, 0, v147, s[10:11]
	v_fmac_f32_dpp v68, v136, v159 row_ror:1 row_mask:0xf bank_mask:0xf
	v_fmac_f32_dpp v48, v137, v161 row_ror:1 row_mask:0xf bank_mask:0xf
	v_fmac_f32_dpp v68, v136, v163 row_ror:2 row_mask:0xf bank_mask:0xf
	v_fmac_f32_dpp v48, v137, v165 row_ror:2 row_mask:0xf bank_mask:0xf
	v_fmac_f32_dpp v70, v138, v160 row_ror:1 row_mask:0xf bank_mask:0xf
	v_fmac_f32_dpp v71, v139, v158 row_ror:1 row_mask:0xf bank_mask:0xf
	v_fmac_f32_dpp v70, v138, v164 row_ror:2 row_mask:0xf bank_mask:0xf
	v_fmac_f32_dpp v71, v139, v162 row_ror:2 row_mask:0xf bank_mask:0xf
	s_nop 0
	v_mov_b32_e32 v69, v48
	v_pk_fma_f32 v[82:83], v[138:139], v[150:151], v[154:155]
	v_pk_fma_f32 v[80:81], v[136:137], v[148:149], v[152:153]
	v_mov_b32_e32 v49, v83
	v_mov_b32_e32 v48, v81
	s_nop 0
	v_fmac_f32_dpp v80, v136, v140 row_shr:1 row_mask:0xf bank_mask:0xf bound_ctrl:1
	v_fmac_f32_dpp v48, v137, v141 row_shr:1 row_mask:0xf bank_mask:0xf bound_ctrl:1
	v_fmac_f32_dpp v80, v136, v144 row_shr:2 row_mask:0xf bank_mask:0xf bound_ctrl:1
	v_fmac_f32_dpp v48, v137, v145 row_shr:2 row_mask:0xf bank_mask:0xf bound_ctrl:1
	v_fmac_f32_dpp v82, v138, v142 row_shr:1 row_mask:0xf bank_mask:0xf bound_ctrl:1
	v_fmac_f32_dpp v49, v139, v143 row_shr:1 row_mask:0xf bank_mask:0xf bound_ctrl:1
	v_fmac_f32_dpp v82, v138, v146 row_shr:2 row_mask:0xf bank_mask:0xf bound_ctrl:1
	v_fmac_f32_dpp v49, v139, v147 row_shr:2 row_mask:0xf bank_mask:0xf bound_ctrl:1
	s_nop 0
	v_fmac_f32_dpp v80, v120, v159 row_ror:1 row_mask:0xf bank_mask:0xf
	v_fmac_f32_dpp v48, v121, v161 row_ror:1 row_mask:0xf bank_mask:0xf
	v_fmac_f32_dpp v80, v120, v163 row_ror:2 row_mask:0xf bank_mask:0xf
	v_fmac_f32_dpp v48, v121, v165 row_ror:2 row_mask:0xf bank_mask:0xf
	v_fmac_f32_dpp v82, v122, v160 row_ror:1 row_mask:0xf bank_mask:0xf
	v_fmac_f32_dpp v49, v123, v158 row_ror:1 row_mask:0xf bank_mask:0xf
	v_fmac_f32_dpp v82, v122, v164 row_ror:2 row_mask:0xf bank_mask:0xf
	v_fmac_f32_dpp v49, v123, v162 row_ror:2 row_mask:0xf bank_mask:0xf
	s_nop 0
	v_mov_b32_e32 v81, v48
	v_mov_b32_e32 v83, v49
	v_pk_fma_f32 v[98:99], v[122:123], v[150:151], v[154:155]
	v_pk_fma_f32 v[96:97], v[120:121], v[148:149], v[152:153]
	v_mov_b32_e32 v48, v99
	s_nop 0
	v_fmac_f32_dpp v96, v120, v140 row_shr:1 row_mask:0xf bank_mask:0xf bound_ctrl:1
	v_fmac_f32_dpp v97, v121, v141 row_shr:1 row_mask:0xf bank_mask:0xf bound_ctrl:1
	v_fmac_f32_dpp v96, v120, v144 row_shr:2 row_mask:0xf bank_mask:0xf bound_ctrl:1
	v_fmac_f32_dpp v97, v121, v145 row_shr:2 row_mask:0xf bank_mask:0xf bound_ctrl:1
	v_fmac_f32_dpp v98, v122, v142 row_shr:1 row_mask:0xf bank_mask:0xf bound_ctrl:1
	v_fmac_f32_dpp v48, v123, v143 row_shr:1 row_mask:0xf bank_mask:0xf bound_ctrl:1
	v_fmac_f32_dpp v98, v122, v146 row_shr:2 row_mask:0xf bank_mask:0xf bound_ctrl:1
	v_fmac_f32_dpp v48, v123, v147 row_shr:2 row_mask:0xf bank_mask:0xf bound_ctrl:1
	s_nop 0
	v_fmac_f32_dpp v96, v132, v159 row_ror:1 row_mask:0xf bank_mask:0xf
	v_fmac_f32_dpp v97, v133, v161 row_ror:1 row_mask:0xf bank_mask:0xf
	v_fmac_f32_dpp v96, v132, v163 row_ror:2 row_mask:0xf bank_mask:0xf
	v_fmac_f32_dpp v97, v133, v165 row_ror:2 row_mask:0xf bank_mask:0xf
	v_fmac_f32_dpp v98, v134, v160 row_ror:1 row_mask:0xf bank_mask:0xf
	v_fmac_f32_dpp v48, v135, v158 row_ror:1 row_mask:0xf bank_mask:0xf
	v_fmac_f32_dpp v98, v134, v164 row_ror:2 row_mask:0xf bank_mask:0xf
	v_fmac_f32_dpp v48, v135, v162 row_ror:2 row_mask:0xf bank_mask:0xf
	s_nop 0
	v_mov_b32_e32 v99, v48
	v_pk_fma_f32 v[48:49], v[134:135], v[150:151], v[154:155]
	v_pk_fma_f32 v[50:51], v[132:133], v[148:149], v[152:153]
	v_mov_b32_e32 v122, v48
	v_mov_b32_e32 v120, v50
	s_nop 1
	v_fmac_f32_dpp v120, v132, v140 row_shr:1 row_mask:0xf bank_mask:0xf bound_ctrl:1
	v_fmac_f32_dpp v51, v133, v141 row_shr:1 row_mask:0xf bank_mask:0xf bound_ctrl:1
	v_fmac_f32_dpp v120, v132, v144 row_shr:2 row_mask:0xf bank_mask:0xf bound_ctrl:1
	v_fmac_f32_dpp v51, v133, v145 row_shr:2 row_mask:0xf bank_mask:0xf bound_ctrl:1
	v_fmac_f32_dpp v122, v134, v142 row_shr:1 row_mask:0xf bank_mask:0xf bound_ctrl:1
	v_fmac_f32_dpp v49, v135, v143 row_shr:1 row_mask:0xf bank_mask:0xf bound_ctrl:1
	v_fmac_f32_dpp v122, v134, v146 row_shr:2 row_mask:0xf bank_mask:0xf bound_ctrl:1
	v_fmac_f32_dpp v49, v135, v147 row_shr:2 row_mask:0xf bank_mask:0xf bound_ctrl:1
	s_and_b64 vcc, exec, s[12:13]
	v_mov_b32_e32 v121, v51
	v_mov_b32_e32 v123, v49
	s_cbranch_vccnz .LBB0_396
	ds_read_b128 v[132:135], v191 offset:16
	ds_read_b128 v[136:139], v193 offset:16
	s_waitcnt lgkmcnt(0)
	v_cndmask_b32_e64 v48, v132, v136, s[8:9]
	v_mul_f32_e32 v48, v163, v48
	v_fmac_f32_e32 v48, v159, v132
	v_add_f32_e32 v120, v120, v48
	v_cndmask_b32_e64 v48, v134, v138, s[8:9]
	v_mul_f32_e32 v48, v164, v48
	v_fmac_f32_e32 v48, v160, v134
	v_cndmask_b32_e64 v50, v133, v137, s[8:9]
	v_add_f32_e32 v122, v122, v48
	v_cndmask_b32_e64 v48, v135, v139, s[8:9]
	v_mul_f32_e32 v50, v165, v50
	v_mul_f32_e32 v48, v162, v48
	v_fmac_f32_e32 v50, v161, v133
	v_fmac_f32_e32 v48, v158, v135
	v_add_f32_e32 v121, v51, v50
	v_add_f32_e32 v123, v49, v48
.LBB0_396:
	v_pk_fma_f32 v[50:51], v[74:75], v[150:151], v[154:155]
	v_pk_fma_f32 v[48:49], v[72:73], v[148:149], v[152:153]
	s_nop 0
	s_nop 0
	v_fmac_f32_dpp v48, v72, v140 row_shr:1 row_mask:0xf bank_mask:0xf bound_ctrl:1
	v_fmac_f32_dpp v49, v73, v141 row_shr:1 row_mask:0xf bank_mask:0xf bound_ctrl:1
	v_fmac_f32_dpp v48, v72, v144 row_shr:2 row_mask:0xf bank_mask:0xf bound_ctrl:1
	v_fmac_f32_dpp v49, v73, v145 row_shr:2 row_mask:0xf bank_mask:0xf bound_ctrl:1
	v_fmac_f32_dpp v50, v74, v142 row_shr:1 row_mask:0xf bank_mask:0xf bound_ctrl:1
	v_fmac_f32_dpp v51, v75, v143 row_shr:1 row_mask:0xf bank_mask:0xf bound_ctrl:1
	v_fmac_f32_dpp v50, v74, v146 row_shr:2 row_mask:0xf bank_mask:0xf bound_ctrl:1
	v_fmac_f32_dpp v51, v75, v147 row_shr:2 row_mask:0xf bank_mask:0xf bound_ctrl:1
	s_nop 0
	v_fmac_f32_dpp v48, v84, v159 row_ror:1 row_mask:0xf bank_mask:0xf
	v_fmac_f32_dpp v49, v85, v161 row_ror:1 row_mask:0xf bank_mask:0xf
	v_fmac_f32_dpp v48, v84, v163 row_ror:2 row_mask:0xf bank_mask:0xf
	v_fmac_f32_dpp v49, v85, v165 row_ror:2 row_mask:0xf bank_mask:0xf
	v_fmac_f32_dpp v50, v86, v160 row_ror:1 row_mask:0xf bank_mask:0xf
	v_fmac_f32_dpp v51, v87, v158 row_ror:1 row_mask:0xf bank_mask:0xf
	v_fmac_f32_dpp v50, v86, v164 row_ror:2 row_mask:0xf bank_mask:0xf
	v_fmac_f32_dpp v51, v87, v162 row_ror:2 row_mask:0xf bank_mask:0xf
	s_nop 0
	v_pk_fma_f32 v[74:75], v[86:87], v[150:151], v[154:155]
	v_pk_fma_f32 v[72:73], v[84:85], v[148:149], v[152:153]
	s_nop 0
	s_nop 0
	v_fmac_f32_dpp v72, v84, v140 row_shr:1 row_mask:0xf bank_mask:0xf bound_ctrl:1
	v_fmac_f32_dpp v73, v85, v141 row_shr:1 row_mask:0xf bank_mask:0xf bound_ctrl:1
	v_fmac_f32_dpp v72, v84, v144 row_shr:2 row_mask:0xf bank_mask:0xf bound_ctrl:1
	v_fmac_f32_dpp v73, v85, v145 row_shr:2 row_mask:0xf bank_mask:0xf bound_ctrl:1
	v_fmac_f32_dpp v74, v86, v142 row_shr:1 row_mask:0xf bank_mask:0xf bound_ctrl:1
	v_fmac_f32_dpp v75, v87, v143 row_shr:1 row_mask:0xf bank_mask:0xf bound_ctrl:1
	v_fmac_f32_dpp v74, v86, v146 row_shr:2 row_mask:0xf bank_mask:0xf bound_ctrl:1
	v_fmac_f32_dpp v75, v87, v147 row_shr:2 row_mask:0xf bank_mask:0xf bound_ctrl:1
	s_nop 0
	v_fmac_f32_dpp v72, v108, v159 row_ror:1 row_mask:0xf bank_mask:0xf
	v_fmac_f32_dpp v73, v109, v161 row_ror:1 row_mask:0xf bank_mask:0xf
	v_fmac_f32_dpp v72, v108, v163 row_ror:2 row_mask:0xf bank_mask:0xf
	v_fmac_f32_dpp v73, v109, v165 row_ror:2 row_mask:0xf bank_mask:0xf
	v_fmac_f32_dpp v74, v110, v160 row_ror:1 row_mask:0xf bank_mask:0xf
	v_fmac_f32_dpp v75, v111, v158 row_ror:1 row_mask:0xf bank_mask:0xf
	v_fmac_f32_dpp v74, v110, v164 row_ror:2 row_mask:0xf bank_mask:0xf
	v_fmac_f32_dpp v75, v111, v162 row_ror:2 row_mask:0xf bank_mask:0xf
	s_nop 0
	v_pk_fma_f32 v[86:87], v[110:111], v[150:151], v[154:155]
	v_pk_fma_f32 v[84:85], v[108:109], v[148:149], v[152:153]
	s_nop 0
	s_nop 0
	v_fmac_f32_dpp v84, v108, v140 row_shr:1 row_mask:0xf bank_mask:0xf bound_ctrl:1
	v_fmac_f32_dpp v85, v109, v141 row_shr:1 row_mask:0xf bank_mask:0xf bound_ctrl:1
	v_fmac_f32_dpp v84, v108, v144 row_shr:2 row_mask:0xf bank_mask:0xf bound_ctrl:1
	v_fmac_f32_dpp v85, v109, v145 row_shr:2 row_mask:0xf bank_mask:0xf bound_ctrl:1
	v_fmac_f32_dpp v86, v110, v142 row_shr:1 row_mask:0xf bank_mask:0xf bound_ctrl:1
	v_fmac_f32_dpp v87, v111, v143 row_shr:1 row_mask:0xf bank_mask:0xf bound_ctrl:1
	v_fmac_f32_dpp v86, v110, v146 row_shr:2 row_mask:0xf bank_mask:0xf bound_ctrl:1
	v_fmac_f32_dpp v87, v111, v147 row_shr:2 row_mask:0xf bank_mask:0xf bound_ctrl:1
	s_nop 0
	v_fmac_f32_dpp v84, v128, v159 row_ror:1 row_mask:0xf bank_mask:0xf
	v_fmac_f32_dpp v85, v129, v161 row_ror:1 row_mask:0xf bank_mask:0xf
	v_fmac_f32_dpp v84, v128, v163 row_ror:2 row_mask:0xf bank_mask:0xf
	v_fmac_f32_dpp v85, v129, v165 row_ror:2 row_mask:0xf bank_mask:0xf
	v_fmac_f32_dpp v86, v130, v160 row_ror:1 row_mask:0xf bank_mask:0xf
	v_fmac_f32_dpp v87, v131, v158 row_ror:1 row_mask:0xf bank_mask:0xf
	v_fmac_f32_dpp v86, v130, v164 row_ror:2 row_mask:0xf bank_mask:0xf
	v_fmac_f32_dpp v87, v131, v162 row_ror:2 row_mask:0xf bank_mask:0xf
	s_nop 0
	v_pk_fma_f32 v[110:111], v[130:131], v[150:151], v[154:155]
	v_pk_fma_f32 v[108:109], v[128:129], v[148:149], v[152:153]
	s_and_b64 vcc, exec, s[14:15]
	s_nop 1
	v_fmac_f32_dpp v108, v128, v140 row_shr:1 row_mask:0xf bank_mask:0xf bound_ctrl:1
	v_fmac_f32_dpp v109, v129, v141 row_shr:1 row_mask:0xf bank_mask:0xf bound_ctrl:1
	v_fmac_f32_dpp v108, v128, v144 row_shr:2 row_mask:0xf bank_mask:0xf bound_ctrl:1
	v_fmac_f32_dpp v109, v129, v145 row_shr:2 row_mask:0xf bank_mask:0xf bound_ctrl:1
	v_fmac_f32_dpp v110, v130, v142 row_shr:1 row_mask:0xf bank_mask:0xf bound_ctrl:1
	v_fmac_f32_dpp v111, v131, v143 row_shr:1 row_mask:0xf bank_mask:0xf bound_ctrl:1
	v_fmac_f32_dpp v110, v130, v146 row_shr:2 row_mask:0xf bank_mask:0xf bound_ctrl:1
	v_fmac_f32_dpp v111, v131, v147 row_shr:2 row_mask:0xf bank_mask:0xf bound_ctrl:1
	s_cbranch_vccnz .LBB0_398
	ds_read_b128 v[128:131], v156 offset:16
	ds_read_b128 v[132:135], v157 offset:16
	s_waitcnt lgkmcnt(0)
	v_cndmask_b32_e64 v132, v128, v132, s[8:9]
	v_mul_f32_e32 v132, v163, v132
	v_fmac_f32_e32 v132, v159, v128
	v_cndmask_b32_e64 v128, v130, v134, s[8:9]
	v_mul_f32_e32 v128, v164, v128
	v_fmac_f32_e32 v128, v160, v130
	v_cndmask_b32_e64 v133, v129, v133, s[8:9]
	v_add_f32_e32 v110, v110, v128
	v_cndmask_b32_e64 v128, v131, v135, s[8:9]
	v_mul_f32_e32 v133, v165, v133
	v_mul_f32_e32 v128, v162, v128
	v_fmac_f32_e32 v133, v161, v129
	v_fmac_f32_e32 v128, v158, v131
	v_add_f32_e32 v108, v108, v132
	v_add_f32_e32 v109, v109, v133
	v_add_f32_e32 v111, v111, v128
.LBB0_398:
	ds_read_b128 v[136:139], v187 offset:9728
	ds_read_b128 v[140:143], v187 offset:8704
	ds_read_b128 v[144:147], v187 offset:10752
	ds_read_b128 v[148:151], v187 offset:11776
	s_add_i32 s54, s4, 0xfffffe00
	s_addk_i32 s4, 0xfa00
	s_waitcnt lgkmcnt(3)
	v_cndmask_b32_e64 v157, 0, v136, s[8:9]
	s_waitcnt lgkmcnt(2)
	v_cndmask_b32_e64 v161, 0, v140, s[10:11]
	s_waitcnt lgkmcnt(0)
	v_pk_fma_f32 v[130:131], v[126:127], v[146:147], v[150:151]
	v_pk_fma_f32 v[128:129], v[124:125], v[144:145], v[148:149]
	v_cndmask_b32_e64 v159, 0, v137, s[8:9]
	s_nop 0
	v_fmac_f32_dpp v128, v124, v136 row_shr:1 row_mask:0xf bank_mask:0xf bound_ctrl:1
	v_fmac_f32_dpp v129, v125, v137 row_shr:1 row_mask:0xf bank_mask:0xf bound_ctrl:1
	v_fmac_f32_dpp v128, v124, v140 row_shr:2 row_mask:0xf bank_mask:0xf bound_ctrl:1
	v_fmac_f32_dpp v129, v125, v141 row_shr:2 row_mask:0xf bank_mask:0xf bound_ctrl:1
	v_fmac_f32_dpp v130, v126, v138 row_shr:1 row_mask:0xf bank_mask:0xf bound_ctrl:1
	v_fmac_f32_dpp v131, v127, v139 row_shr:1 row_mask:0xf bank_mask:0xf bound_ctrl:1
	v_fmac_f32_dpp v130, v126, v142 row_shr:2 row_mask:0xf bank_mask:0xf bound_ctrl:1
	v_fmac_f32_dpp v131, v127, v143 row_shr:2 row_mask:0xf bank_mask:0xf bound_ctrl:1
	v_cndmask_b32_e64 v163, 0, v141, s[10:11]
	v_cndmask_b32_e64 v158, 0, v138, s[8:9]
	v_cndmask_b32_e64 v162, 0, v142, s[10:11]
	v_cndmask_b32_e64 v156, 0, v139, s[8:9]
	v_cndmask_b32_e64 v160, 0, v143, s[10:11]
	v_add_u32_e32 v154, s54, v189
	v_add_u32_e32 v155, s4, v189
	v_fmac_f32_dpp v128, v112, v157 row_ror:1 row_mask:0xf bank_mask:0xf
	v_fmac_f32_dpp v129, v113, v159 row_ror:1 row_mask:0xf bank_mask:0xf
	v_fmac_f32_dpp v128, v112, v161 row_ror:2 row_mask:0xf bank_mask:0xf
	v_fmac_f32_dpp v129, v113, v163 row_ror:2 row_mask:0xf bank_mask:0xf
	v_fmac_f32_dpp v130, v114, v158 row_ror:1 row_mask:0xf bank_mask:0xf
	v_fmac_f32_dpp v131, v115, v156 row_ror:1 row_mask:0xf bank_mask:0xf
	v_fmac_f32_dpp v130, v114, v162 row_ror:2 row_mask:0xf bank_mask:0xf
	v_fmac_f32_dpp v131, v115, v160 row_ror:2 row_mask:0xf bank_mask:0xf
	s_nop 0
	v_pk_fma_f32 v[126:127], v[114:115], v[146:147], v[150:151]
	v_pk_fma_f32 v[124:125], v[112:113], v[144:145], v[148:149]
	s_nop 0
	s_nop 0
	v_fmac_f32_dpp v124, v112, v136 row_shr:1 row_mask:0xf bank_mask:0xf bound_ctrl:1
	v_fmac_f32_dpp v125, v113, v137 row_shr:1 row_mask:0xf bank_mask:0xf bound_ctrl:1
	v_fmac_f32_dpp v124, v112, v140 row_shr:2 row_mask:0xf bank_mask:0xf bound_ctrl:1
	v_fmac_f32_dpp v125, v113, v141 row_shr:2 row_mask:0xf bank_mask:0xf bound_ctrl:1
	v_mov_b32_e32 v112, v127
	s_nop 0
	v_fmac_f32_dpp v126, v114, v138 row_shr:1 row_mask:0xf bank_mask:0xf bound_ctrl:1
	v_fmac_f32_dpp v112, v115, v139 row_shr:1 row_mask:0xf bank_mask:0xf bound_ctrl:1
	v_fmac_f32_dpp v126, v114, v142 row_shr:2 row_mask:0xf bank_mask:0xf bound_ctrl:1
	v_fmac_f32_dpp v112, v115, v143 row_shr:2 row_mask:0xf bank_mask:0xf bound_ctrl:1
	v_fmac_f32_dpp v124, v100, v157 row_ror:1 row_mask:0xf bank_mask:0xf
	v_fmac_f32_dpp v125, v101, v159 row_ror:1 row_mask:0xf bank_mask:0xf
	v_fmac_f32_dpp v124, v100, v161 row_ror:2 row_mask:0xf bank_mask:0xf
	v_fmac_f32_dpp v125, v101, v163 row_ror:2 row_mask:0xf bank_mask:0xf
	s_nop 0
	v_fmac_f32_dpp v126, v102, v158 row_ror:1 row_mask:0xf bank_mask:0xf
	v_fmac_f32_dpp v112, v103, v156 row_ror:1 row_mask:0xf bank_mask:0xf
	v_fmac_f32_dpp v126, v102, v162 row_ror:2 row_mask:0xf bank_mask:0xf
	v_fmac_f32_dpp v112, v103, v160 row_ror:2 row_mask:0xf bank_mask:0xf
	s_nop 0
	v_mov_b32_e32 v127, v112
	v_pk_fma_f32 v[114:115], v[102:103], v[146:147], v[150:151]
	v_pk_fma_f32 v[112:113], v[100:101], v[144:145], v[148:149]
	s_nop 0
	s_nop 0
	v_fmac_f32_dpp v112, v100, v136 row_shr:1 row_mask:0xf bank_mask:0xf bound_ctrl:1
	v_fmac_f32_dpp v113, v101, v137 row_shr:1 row_mask:0xf bank_mask:0xf bound_ctrl:1
	v_fmac_f32_dpp v112, v100, v140 row_shr:2 row_mask:0xf bank_mask:0xf bound_ctrl:1
	v_fmac_f32_dpp v113, v101, v141 row_shr:2 row_mask:0xf bank_mask:0xf bound_ctrl:1
	v_fmac_f32_dpp v114, v102, v138 row_shr:1 row_mask:0xf bank_mask:0xf bound_ctrl:1
	v_fmac_f32_dpp v115, v103, v139 row_shr:1 row_mask:0xf bank_mask:0xf bound_ctrl:1
	v_fmac_f32_dpp v114, v102, v142 row_shr:2 row_mask:0xf bank_mask:0xf bound_ctrl:1
	v_fmac_f32_dpp v115, v103, v143 row_shr:2 row_mask:0xf bank_mask:0xf bound_ctrl:1
	s_nop 0
	v_fmac_f32_dpp v112, v88, v157 row_ror:1 row_mask:0xf bank_mask:0xf
	v_fmac_f32_dpp v113, v89, v159 row_ror:1 row_mask:0xf bank_mask:0xf
	v_fmac_f32_dpp v112, v88, v161 row_ror:2 row_mask:0xf bank_mask:0xf
	v_fmac_f32_dpp v113, v89, v163 row_ror:2 row_mask:0xf bank_mask:0xf
	v_fmac_f32_dpp v114, v90, v158 row_ror:1 row_mask:0xf bank_mask:0xf
	v_fmac_f32_dpp v115, v91, v156 row_ror:1 row_mask:0xf bank_mask:0xf
	v_fmac_f32_dpp v114, v90, v162 row_ror:2 row_mask:0xf bank_mask:0xf
	v_fmac_f32_dpp v115, v91, v160 row_ror:2 row_mask:0xf bank_mask:0xf
	s_nop 0
	v_pk_fma_f32 v[100:101], v[90:91], v[146:147], v[150:151]
	v_pk_fma_f32 v[102:103], v[88:89], v[144:145], v[148:149]
	v_mov_b32_e32 v134, v100
	v_mov_b32_e32 v132, v102
	s_nop 1
	v_fmac_f32_dpp v132, v88, v136 row_shr:1 row_mask:0xf bank_mask:0xf bound_ctrl:1
	v_fmac_f32_dpp v103, v89, v137 row_shr:1 row_mask:0xf bank_mask:0xf bound_ctrl:1
	v_fmac_f32_dpp v132, v88, v140 row_shr:2 row_mask:0xf bank_mask:0xf bound_ctrl:1
	v_fmac_f32_dpp v103, v89, v141 row_shr:2 row_mask:0xf bank_mask:0xf bound_ctrl:1
	v_fmac_f32_dpp v134, v90, v138 row_shr:1 row_mask:0xf bank_mask:0xf bound_ctrl:1
	v_fmac_f32_dpp v101, v91, v139 row_shr:1 row_mask:0xf bank_mask:0xf bound_ctrl:1
	v_fmac_f32_dpp v134, v90, v142 row_shr:2 row_mask:0xf bank_mask:0xf bound_ctrl:1
	v_fmac_f32_dpp v101, v91, v143 row_shr:2 row_mask:0xf bank_mask:0xf bound_ctrl:1
	s_and_b64 vcc, exec, s[12:13]
	v_mov_b32_e32 v133, v103
	v_mov_b32_e32 v135, v101
	s_cbranch_vccnz .LBB0_400
	ds_read_b128 v[88:91], v154
	ds_read_b128 v[164:167], v155
	s_waitcnt lgkmcnt(0)
	v_cndmask_b32_e64 v100, v88, v164, s[8:9]
	v_mul_f32_e32 v100, v161, v100
	v_fmac_f32_e32 v100, v157, v88
	v_cndmask_b32_e64 v88, v90, v166, s[8:9]
	v_mul_f32_e32 v88, v162, v88
	v_fmac_f32_e32 v88, v158, v90
	v_cndmask_b32_e64 v102, v89, v165, s[8:9]
	v_add_f32_e32 v134, v134, v88
	v_cndmask_b32_e64 v88, v91, v167, s[8:9]
	v_mul_f32_e32 v102, v163, v102
	v_mul_f32_e32 v88, v160, v88
	v_fmac_f32_e32 v102, v159, v89
	v_fmac_f32_e32 v88, v156, v91
	v_add_f32_e32 v132, v132, v100
	v_add_f32_e32 v133, v103, v102
	v_add_f32_e32 v135, v101, v88
.LBB0_400:
	v_pk_fma_f32 v[90:91], v[118:119], v[146:147], v[150:151]
	v_pk_fma_f32 v[88:89], v[116:117], v[144:145], v[148:149]
	s_add_i32 s4, s5, 0xfffffe00
	s_addk_i32 s5, 0xfa00
	v_fmac_f32_dpp v88, v116, v136 row_shr:1 row_mask:0xf bank_mask:0xf bound_ctrl:1
	v_fmac_f32_dpp v89, v117, v137 row_shr:1 row_mask:0xf bank_mask:0xf bound_ctrl:1
	v_fmac_f32_dpp v88, v116, v140 row_shr:2 row_mask:0xf bank_mask:0xf bound_ctrl:1
	v_fmac_f32_dpp v89, v117, v141 row_shr:2 row_mask:0xf bank_mask:0xf bound_ctrl:1
	v_fmac_f32_dpp v90, v118, v138 row_shr:1 row_mask:0xf bank_mask:0xf bound_ctrl:1
	v_fmac_f32_dpp v91, v119, v139 row_shr:1 row_mask:0xf bank_mask:0xf bound_ctrl:1
	v_fmac_f32_dpp v90, v118, v142 row_shr:2 row_mask:0xf bank_mask:0xf bound_ctrl:1
	v_fmac_f32_dpp v91, v119, v143 row_shr:2 row_mask:0xf bank_mask:0xf bound_ctrl:1
	v_add_u32_e32 v152, s4, v189
	v_add_u32_e32 v153, s5, v189
	v_fmac_f32_dpp v88, v104, v157 row_ror:1 row_mask:0xf bank_mask:0xf
	v_fmac_f32_dpp v89, v105, v159 row_ror:1 row_mask:0xf bank_mask:0xf
	v_fmac_f32_dpp v88, v104, v161 row_ror:2 row_mask:0xf bank_mask:0xf
	v_fmac_f32_dpp v89, v105, v163 row_ror:2 row_mask:0xf bank_mask:0xf
	v_fmac_f32_dpp v90, v106, v158 row_ror:1 row_mask:0xf bank_mask:0xf
	v_fmac_f32_dpp v91, v107, v156 row_ror:1 row_mask:0xf bank_mask:0xf
	v_fmac_f32_dpp v90, v106, v162 row_ror:2 row_mask:0xf bank_mask:0xf
	v_fmac_f32_dpp v91, v107, v160 row_ror:2 row_mask:0xf bank_mask:0xf
	s_nop 0
	v_pk_fma_f32 v[102:103], v[106:107], v[146:147], v[150:151]
	v_pk_fma_f32 v[100:101], v[104:105], v[144:145], v[148:149]
	s_nop 0
	s_nop 0
	v_fmac_f32_dpp v100, v104, v136 row_shr:1 row_mask:0xf bank_mask:0xf bound_ctrl:1
	v_fmac_f32_dpp v101, v105, v137 row_shr:1 row_mask:0xf bank_mask:0xf bound_ctrl:1
	v_fmac_f32_dpp v100, v104, v140 row_shr:2 row_mask:0xf bank_mask:0xf bound_ctrl:1
	v_fmac_f32_dpp v101, v105, v141 row_shr:2 row_mask:0xf bank_mask:0xf bound_ctrl:1
	v_fmac_f32_dpp v102, v106, v138 row_shr:1 row_mask:0xf bank_mask:0xf bound_ctrl:1
	v_fmac_f32_dpp v103, v107, v139 row_shr:1 row_mask:0xf bank_mask:0xf bound_ctrl:1
	v_fmac_f32_dpp v102, v106, v142 row_shr:2 row_mask:0xf bank_mask:0xf bound_ctrl:1
	v_fmac_f32_dpp v103, v107, v143 row_shr:2 row_mask:0xf bank_mask:0xf bound_ctrl:1
	s_nop 0
	v_fmac_f32_dpp v100, v92, v157 row_ror:1 row_mask:0xf bank_mask:0xf
	v_fmac_f32_dpp v101, v93, v159 row_ror:1 row_mask:0xf bank_mask:0xf
	v_fmac_f32_dpp v100, v92, v161 row_ror:2 row_mask:0xf bank_mask:0xf
	v_fmac_f32_dpp v101, v93, v163 row_ror:2 row_mask:0xf bank_mask:0xf
	v_fmac_f32_dpp v102, v94, v158 row_ror:1 row_mask:0xf bank_mask:0xf
	v_fmac_f32_dpp v103, v95, v156 row_ror:1 row_mask:0xf bank_mask:0xf
	v_fmac_f32_dpp v102, v94, v162 row_ror:2 row_mask:0xf bank_mask:0xf
	v_fmac_f32_dpp v103, v95, v160 row_ror:2 row_mask:0xf bank_mask:0xf
	s_nop 0
	v_pk_fma_f32 v[106:107], v[94:95], v[146:147], v[150:151]
	v_pk_fma_f32 v[104:105], v[92:93], v[144:145], v[148:149]
	s_nop 0
	s_nop 0
	v_fmac_f32_dpp v104, v92, v136 row_shr:1 row_mask:0xf bank_mask:0xf bound_ctrl:1
	v_fmac_f32_dpp v105, v93, v137 row_shr:1 row_mask:0xf bank_mask:0xf bound_ctrl:1
	v_fmac_f32_dpp v104, v92, v140 row_shr:2 row_mask:0xf bank_mask:0xf bound_ctrl:1
	v_fmac_f32_dpp v105, v93, v141 row_shr:2 row_mask:0xf bank_mask:0xf bound_ctrl:1
	v_fmac_f32_dpp v106, v94, v138 row_shr:1 row_mask:0xf bank_mask:0xf bound_ctrl:1
	v_fmac_f32_dpp v107, v95, v139 row_shr:1 row_mask:0xf bank_mask:0xf bound_ctrl:1
	v_fmac_f32_dpp v106, v94, v142 row_shr:2 row_mask:0xf bank_mask:0xf bound_ctrl:1
	v_fmac_f32_dpp v107, v95, v143 row_shr:2 row_mask:0xf bank_mask:0xf bound_ctrl:1
	s_nop 0
	v_fmac_f32_dpp v104, v76, v157 row_ror:1 row_mask:0xf bank_mask:0xf
	v_fmac_f32_dpp v105, v77, v159 row_ror:1 row_mask:0xf bank_mask:0xf
	v_fmac_f32_dpp v104, v76, v161 row_ror:2 row_mask:0xf bank_mask:0xf
	v_fmac_f32_dpp v105, v77, v163 row_ror:2 row_mask:0xf bank_mask:0xf
	v_fmac_f32_dpp v106, v78, v158 row_ror:1 row_mask:0xf bank_mask:0xf
	v_fmac_f32_dpp v107, v79, v156 row_ror:1 row_mask:0xf bank_mask:0xf
	v_fmac_f32_dpp v106, v78, v162 row_ror:2 row_mask:0xf bank_mask:0xf
	v_fmac_f32_dpp v107, v79, v160 row_ror:2 row_mask:0xf bank_mask:0xf
	s_nop 0
	v_pk_fma_f32 v[94:95], v[78:79], v[146:147], v[150:151]
	v_pk_fma_f32 v[92:93], v[76:77], v[144:145], v[148:149]
	s_and_b64 vcc, exec, s[14:15]
	s_nop 1
	v_fmac_f32_dpp v92, v76, v136 row_shr:1 row_mask:0xf bank_mask:0xf bound_ctrl:1
	v_fmac_f32_dpp v93, v77, v137 row_shr:1 row_mask:0xf bank_mask:0xf bound_ctrl:1
	v_fmac_f32_dpp v92, v76, v140 row_shr:2 row_mask:0xf bank_mask:0xf bound_ctrl:1
	v_fmac_f32_dpp v93, v77, v141 row_shr:2 row_mask:0xf bank_mask:0xf bound_ctrl:1
	v_mov_b32_e32 v76, v95
	s_nop 0
	v_fmac_f32_dpp v94, v78, v138 row_shr:1 row_mask:0xf bank_mask:0xf bound_ctrl:1
	v_fmac_f32_dpp v76, v79, v139 row_shr:1 row_mask:0xf bank_mask:0xf bound_ctrl:1
	v_fmac_f32_dpp v94, v78, v142 row_shr:2 row_mask:0xf bank_mask:0xf bound_ctrl:1
	v_fmac_f32_dpp v76, v79, v143 row_shr:2 row_mask:0xf bank_mask:0xf bound_ctrl:1
	s_cbranch_vccnz .LBB0_402
	ds_read_b128 v[116:119], v152
	ds_read_b128 v[136:139], v153
	s_waitcnt lgkmcnt(0)
	v_cndmask_b32_e64 v77, v116, v136, s[8:9]
	v_mul_f32_e32 v77, v161, v77
	v_fmac_f32_e32 v77, v157, v116
	v_add_f32_e32 v92, v92, v77
	v_cndmask_b32_e64 v77, v118, v138, s[8:9]
	v_mul_f32_e32 v77, v162, v77
	v_fmac_f32_e32 v77, v158, v118
	v_cndmask_b32_e64 v78, v117, v137, s[8:9]
	v_add_f32_e32 v94, v94, v77
	v_cndmask_b32_e64 v77, v119, v139, s[8:9]
	v_mul_f32_e32 v78, v163, v78
	v_mul_f32_e32 v77, v160, v77
	v_fmac_f32_e32 v78, v159, v117
	v_fmac_f32_e32 v77, v156, v119
	v_add_f32_e32 v93, v93, v78
	v_add_f32_e32 v95, v76, v77
	s_branch .LBB0_403

.LBB0_403:
	ds_read_b128 v[116:119], v187 offset:9744
	ds_read_b128 v[136:139], v187 offset:8720
	ds_read_b128 v[140:143], v187 offset:10768
	ds_read_b128 v[144:147], v187 offset:11792
	s_waitcnt lgkmcnt(3)
	v_cndmask_b32_e64 v157, 0, v116, s[8:9]
	s_waitcnt lgkmcnt(2)
	v_cndmask_b32_e64 v161, 0, v136, s[10:11]
	v_cndmask_b32_e64 v159, 0, v117, s[8:9]
	s_waitcnt lgkmcnt(0)
	v_pk_fma_f32 v[78:79], v[66:67], v[142:143], v[146:147]
	v_pk_fma_f32 v[76:77], v[64:65], v[140:141], v[144:145]
	v_cndmask_b32_e64 v163, 0, v137, s[10:11]
	s_nop 0
	v_fmac_f32_dpp v76, v64, v116 row_shr:1 row_mask:0xf bank_mask:0xf bound_ctrl:1
	v_fmac_f32_dpp v77, v65, v117 row_shr:1 row_mask:0xf bank_mask:0xf bound_ctrl:1
	v_fmac_f32_dpp v76, v64, v136 row_shr:2 row_mask:0xf bank_mask:0xf bound_ctrl:1
	v_fmac_f32_dpp v77, v65, v137 row_shr:2 row_mask:0xf bank_mask:0xf bound_ctrl:1
	v_fmac_f32_dpp v78, v66, v118 row_shr:1 row_mask:0xf bank_mask:0xf bound_ctrl:1
	v_fmac_f32_dpp v79, v67, v119 row_shr:1 row_mask:0xf bank_mask:0xf bound_ctrl:1
	v_fmac_f32_dpp v78, v66, v138 row_shr:2 row_mask:0xf bank_mask:0xf bound_ctrl:1
	v_fmac_f32_dpp v79, v67, v139 row_shr:2 row_mask:0xf bank_mask:0xf bound_ctrl:1
	v_cndmask_b32_e64 v158, 0, v118, s[8:9]
	v_cndmask_b32_e64 v162, 0, v138, s[10:11]
	v_cndmask_b32_e64 v156, 0, v119, s[8:9]
	v_cndmask_b32_e64 v160, 0, v139, s[10:11]
	v_fmac_f32_dpp v76, v52, v157 row_ror:1 row_mask:0xf bank_mask:0xf
	v_fmac_f32_dpp v77, v53, v159 row_ror:1 row_mask:0xf bank_mask:0xf
	v_fmac_f32_dpp v76, v52, v161 row_ror:2 row_mask:0xf bank_mask:0xf
	v_fmac_f32_dpp v77, v53, v163 row_ror:2 row_mask:0xf bank_mask:0xf
	v_fmac_f32_dpp v78, v54, v158 row_ror:1 row_mask:0xf bank_mask:0xf
	v_fmac_f32_dpp v79, v55, v156 row_ror:1 row_mask:0xf bank_mask:0xf
	v_fmac_f32_dpp v78, v54, v162 row_ror:2 row_mask:0xf bank_mask:0xf
	v_fmac_f32_dpp v79, v55, v160 row_ror:2 row_mask:0xf bank_mask:0xf
	s_nop 0
	v_pk_fma_f32 v[66:67], v[54:55], v[142:143], v[146:147]
	v_pk_fma_f32 v[64:65], v[52:53], v[140:141], v[144:145]
	s_nop 0
	s_nop 0
	v_fmac_f32_dpp v64, v52, v116 row_shr:1 row_mask:0xf bank_mask:0xf bound_ctrl:1
	v_fmac_f32_dpp v65, v53, v117 row_shr:1 row_mask:0xf bank_mask:0xf bound_ctrl:1
	v_fmac_f32_dpp v64, v52, v136 row_shr:2 row_mask:0xf bank_mask:0xf bound_ctrl:1
	v_fmac_f32_dpp v65, v53, v137 row_shr:2 row_mask:0xf bank_mask:0xf bound_ctrl:1
	v_mov_b32_e32 v52, v67
	s_nop 0
	v_fmac_f32_dpp v66, v54, v118 row_shr:1 row_mask:0xf bank_mask:0xf bound_ctrl:1
	v_fmac_f32_dpp v52, v55, v119 row_shr:1 row_mask:0xf bank_mask:0xf bound_ctrl:1
	v_fmac_f32_dpp v66, v54, v138 row_shr:2 row_mask:0xf bank_mask:0xf bound_ctrl:1
	v_fmac_f32_dpp v52, v55, v139 row_shr:2 row_mask:0xf bank_mask:0xf bound_ctrl:1
	v_fmac_f32_dpp v64, v36, v157 row_ror:1 row_mask:0xf bank_mask:0xf
	v_fmac_f32_dpp v65, v37, v159 row_ror:1 row_mask:0xf bank_mask:0xf
	v_fmac_f32_dpp v64, v36, v161 row_ror:2 row_mask:0xf bank_mask:0xf
	v_fmac_f32_dpp v65, v37, v163 row_ror:2 row_mask:0xf bank_mask:0xf
	s_nop 0
	v_fmac_f32_dpp v66, v38, v158 row_ror:1 row_mask:0xf bank_mask:0xf
	v_fmac_f32_dpp v52, v39, v156 row_ror:1 row_mask:0xf bank_mask:0xf
	v_fmac_f32_dpp v66, v38, v162 row_ror:2 row_mask:0xf bank_mask:0xf
	v_fmac_f32_dpp v52, v39, v160 row_ror:2 row_mask:0xf bank_mask:0xf
	s_nop 0
	v_mov_b32_e32 v67, v52
	v_pk_fma_f32 v[54:55], v[38:39], v[142:143], v[146:147]
	v_pk_fma_f32 v[52:53], v[36:37], v[140:141], v[144:145]
	s_nop 0
	s_nop 0
	v_fmac_f32_dpp v52, v36, v116 row_shr:1 row_mask:0xf bank_mask:0xf bound_ctrl:1
	v_fmac_f32_dpp v53, v37, v117 row_shr:1 row_mask:0xf bank_mask:0xf bound_ctrl:1
	v_fmac_f32_dpp v52, v36, v136 row_shr:2 row_mask:0xf bank_mask:0xf bound_ctrl:1
	v_fmac_f32_dpp v53, v37, v137 row_shr:2 row_mask:0xf bank_mask:0xf bound_ctrl:1
	v_mov_b32_e32 v36, v55
	s_nop 0
	v_fmac_f32_dpp v54, v38, v118 row_shr:1 row_mask:0xf bank_mask:0xf bound_ctrl:1
	v_fmac_f32_dpp v36, v39, v119 row_shr:1 row_mask:0xf bank_mask:0xf bound_ctrl:1
	v_fmac_f32_dpp v54, v38, v138 row_shr:2 row_mask:0xf bank_mask:0xf bound_ctrl:1
	v_fmac_f32_dpp v36, v39, v139 row_shr:2 row_mask:0xf bank_mask:0xf bound_ctrl:1
	v_fmac_f32_dpp v52, v24, v157 row_ror:1 row_mask:0xf bank_mask:0xf
	v_fmac_f32_dpp v53, v25, v159 row_ror:1 row_mask:0xf bank_mask:0xf
	v_fmac_f32_dpp v52, v24, v161 row_ror:2 row_mask:0xf bank_mask:0xf
	v_fmac_f32_dpp v53, v25, v163 row_ror:2 row_mask:0xf bank_mask:0xf
	s_nop 0
	v_fmac_f32_dpp v54, v26, v158 row_ror:1 row_mask:0xf bank_mask:0xf
	v_fmac_f32_dpp v36, v27, v156 row_ror:1 row_mask:0xf bank_mask:0xf
	v_fmac_f32_dpp v54, v26, v162 row_ror:2 row_mask:0xf bank_mask:0xf
	v_fmac_f32_dpp v36, v27, v160 row_ror:2 row_mask:0xf bank_mask:0xf
	s_nop 0
	v_mov_b32_e32 v55, v36
	v_pk_fma_f32 v[36:37], v[26:27], v[142:143], v[146:147]
	v_pk_fma_f32 v[38:39], v[24:25], v[140:141], v[144:145]
	v_mov_b32_e32 v150, v36
	v_mov_b32_e32 v148, v38
	s_nop 1
	v_fmac_f32_dpp v148, v24, v116 row_shr:1 row_mask:0xf bank_mask:0xf bound_ctrl:1
	v_fmac_f32_dpp v39, v25, v117 row_shr:1 row_mask:0xf bank_mask:0xf bound_ctrl:1
	v_fmac_f32_dpp v148, v24, v136 row_shr:2 row_mask:0xf bank_mask:0xf bound_ctrl:1
	v_fmac_f32_dpp v39, v25, v137 row_shr:2 row_mask:0xf bank_mask:0xf bound_ctrl:1
	v_fmac_f32_dpp v150, v26, v118 row_shr:1 row_mask:0xf bank_mask:0xf bound_ctrl:1
	v_fmac_f32_dpp v37, v27, v119 row_shr:1 row_mask:0xf bank_mask:0xf bound_ctrl:1
	v_fmac_f32_dpp v150, v26, v138 row_shr:2 row_mask:0xf bank_mask:0xf bound_ctrl:1
	v_fmac_f32_dpp v37, v27, v139 row_shr:2 row_mask:0xf bank_mask:0xf bound_ctrl:1
	s_and_b64 vcc, exec, s[12:13]
	v_mov_b32_e32 v149, v39
	v_mov_b32_e32 v151, v37
	s_cbranch_vccnz .LBB0_405
	ds_read_b128 v[24:27], v154 offset:16
	ds_read_b128 v[164:167], v155 offset:16
	s_waitcnt lgkmcnt(0)
	v_cndmask_b32_e64 v36, v24, v164, s[8:9]
	v_mul_f32_e32 v36, v161, v36
	v_fmac_f32_e32 v36, v157, v24
	v_cndmask_b32_e64 v24, v26, v166, s[8:9]
	v_mul_f32_e32 v24, v162, v24
	v_fmac_f32_e32 v24, v158, v26
	v_cndmask_b32_e64 v38, v25, v165, s[8:9]
	v_add_f32_e32 v150, v150, v24
	v_cndmask_b32_e64 v24, v27, v167, s[8:9]
	v_mul_f32_e32 v38, v163, v38
	v_mul_f32_e32 v24, v160, v24
	v_fmac_f32_e32 v38, v159, v25
	v_fmac_f32_e32 v24, v156, v27
	v_add_f32_e32 v148, v148, v36
	v_add_f32_e32 v149, v39, v38
	v_add_f32_e32 v151, v37, v24
.LBB0_405:
	v_pk_fma_f32 v[26:27], v[58:59], v[142:143], v[146:147]
	v_pk_fma_f32 v[24:25], v[56:57], v[140:141], v[144:145]
	s_nop 0
	s_nop 0
	v_fmac_f32_dpp v24, v56, v116 row_shr:1 row_mask:0xf bank_mask:0xf bound_ctrl:1
	v_fmac_f32_dpp v25, v57, v117 row_shr:1 row_mask:0xf bank_mask:0xf bound_ctrl:1
	v_fmac_f32_dpp v24, v56, v136 row_shr:2 row_mask:0xf bank_mask:0xf bound_ctrl:1
	v_fmac_f32_dpp v25, v57, v137 row_shr:2 row_mask:0xf bank_mask:0xf bound_ctrl:1
	v_fmac_f32_dpp v26, v58, v118 row_shr:1 row_mask:0xf bank_mask:0xf bound_ctrl:1
	v_fmac_f32_dpp v27, v59, v119 row_shr:1 row_mask:0xf bank_mask:0xf bound_ctrl:1
	v_fmac_f32_dpp v26, v58, v138 row_shr:2 row_mask:0xf bank_mask:0xf bound_ctrl:1
	v_fmac_f32_dpp v27, v59, v139 row_shr:2 row_mask:0xf bank_mask:0xf bound_ctrl:1
	s_nop 0
	v_fmac_f32_dpp v24, v44, v157 row_ror:1 row_mask:0xf bank_mask:0xf
	v_fmac_f32_dpp v25, v45, v159 row_ror:1 row_mask:0xf bank_mask:0xf
	v_fmac_f32_dpp v24, v44, v161 row_ror:2 row_mask:0xf bank_mask:0xf
	v_fmac_f32_dpp v25, v45, v163 row_ror:2 row_mask:0xf bank_mask:0xf
	v_fmac_f32_dpp v26, v46, v158 row_ror:1 row_mask:0xf bank_mask:0xf
	v_fmac_f32_dpp v27, v47, v156 row_ror:1 row_mask:0xf bank_mask:0xf
	v_fmac_f32_dpp v26, v46, v162 row_ror:2 row_mask:0xf bank_mask:0xf
	v_fmac_f32_dpp v27, v47, v160 row_ror:2 row_mask:0xf bank_mask:0xf
	s_nop 0
	v_pk_fma_f32 v[38:39], v[46:47], v[142:143], v[146:147]
	v_pk_fma_f32 v[36:37], v[44:45], v[140:141], v[144:145]
	s_nop 0
	s_nop 0
	v_fmac_f32_dpp v36, v44, v116 row_shr:1 row_mask:0xf bank_mask:0xf bound_ctrl:1
	v_fmac_f32_dpp v37, v45, v117 row_shr:1 row_mask:0xf bank_mask:0xf bound_ctrl:1
	v_fmac_f32_dpp v36, v44, v136 row_shr:2 row_mask:0xf bank_mask:0xf bound_ctrl:1
	v_fmac_f32_dpp v37, v45, v137 row_shr:2 row_mask:0xf bank_mask:0xf bound_ctrl:1
	v_fmac_f32_dpp v38, v46, v118 row_shr:1 row_mask:0xf bank_mask:0xf bound_ctrl:1
	v_fmac_f32_dpp v39, v47, v119 row_shr:1 row_mask:0xf bank_mask:0xf bound_ctrl:1
	v_fmac_f32_dpp v38, v46, v138 row_shr:2 row_mask:0xf bank_mask:0xf bound_ctrl:1
	v_fmac_f32_dpp v39, v47, v139 row_shr:2 row_mask:0xf bank_mask:0xf bound_ctrl:1
	s_nop 0
	v_fmac_f32_dpp v36, v28, v157 row_ror:1 row_mask:0xf bank_mask:0xf
	v_fmac_f32_dpp v37, v29, v159 row_ror:1 row_mask:0xf bank_mask:0xf
	v_fmac_f32_dpp v36, v28, v161 row_ror:2 row_mask:0xf bank_mask:0xf
	v_fmac_f32_dpp v37, v29, v163 row_ror:2 row_mask:0xf bank_mask:0xf
	v_fmac_f32_dpp v38, v30, v158 row_ror:1 row_mask:0xf bank_mask:0xf
	v_fmac_f32_dpp v39, v31, v156 row_ror:1 row_mask:0xf bank_mask:0xf
	v_fmac_f32_dpp v38, v30, v162 row_ror:2 row_mask:0xf bank_mask:0xf
	v_fmac_f32_dpp v39, v31, v160 row_ror:2 row_mask:0xf bank_mask:0xf
	s_nop 0
	v_pk_fma_f32 v[46:47], v[30:31], v[142:143], v[146:147]
	v_pk_fma_f32 v[44:45], v[28:29], v[140:141], v[144:145]
	s_nop 0
	s_nop 0
	v_fmac_f32_dpp v44, v28, v116 row_shr:1 row_mask:0xf bank_mask:0xf bound_ctrl:1
	v_fmac_f32_dpp v45, v29, v117 row_shr:1 row_mask:0xf bank_mask:0xf bound_ctrl:1
	v_fmac_f32_dpp v44, v28, v136 row_shr:2 row_mask:0xf bank_mask:0xf bound_ctrl:1
	v_fmac_f32_dpp v45, v29, v137 row_shr:2 row_mask:0xf bank_mask:0xf bound_ctrl:1
	v_fmac_f32_dpp v46, v30, v118 row_shr:1 row_mask:0xf bank_mask:0xf bound_ctrl:1
	v_fmac_f32_dpp v47, v31, v119 row_shr:1 row_mask:0xf bank_mask:0xf bound_ctrl:1
	v_fmac_f32_dpp v46, v30, v138 row_shr:2 row_mask:0xf bank_mask:0xf bound_ctrl:1
	v_fmac_f32_dpp v47, v31, v139 row_shr:2 row_mask:0xf bank_mask:0xf bound_ctrl:1
	s_nop 0
	v_fmac_f32_dpp v44, v12, v157 row_ror:1 row_mask:0xf bank_mask:0xf
	v_fmac_f32_dpp v45, v13, v159 row_ror:1 row_mask:0xf bank_mask:0xf
	v_fmac_f32_dpp v44, v12, v161 row_ror:2 row_mask:0xf bank_mask:0xf
	v_fmac_f32_dpp v45, v13, v163 row_ror:2 row_mask:0xf bank_mask:0xf
	v_fmac_f32_dpp v46, v14, v158 row_ror:1 row_mask:0xf bank_mask:0xf
	v_fmac_f32_dpp v47, v15, v156 row_ror:1 row_mask:0xf bank_mask:0xf
	v_fmac_f32_dpp v46, v14, v162 row_ror:2 row_mask:0xf bank_mask:0xf
	v_fmac_f32_dpp v47, v15, v160 row_ror:2 row_mask:0xf bank_mask:0xf
	s_nop 0
	v_pk_fma_f32 v[30:31], v[14:15], v[142:143], v[146:147]
	v_pk_fma_f32 v[28:29], v[12:13], v[140:141], v[144:145]
	s_and_b64 vcc, exec, s[14:15]
	s_nop 1
	v_fmac_f32_dpp v28, v12, v116 row_shr:1 row_mask:0xf bank_mask:0xf bound_ctrl:1
	v_fmac_f32_dpp v29, v13, v117 row_shr:1 row_mask:0xf bank_mask:0xf bound_ctrl:1
	v_fmac_f32_dpp v28, v12, v136 row_shr:2 row_mask:0xf bank_mask:0xf bound_ctrl:1
	v_fmac_f32_dpp v29, v13, v137 row_shr:2 row_mask:0xf bank_mask:0xf bound_ctrl:1
	v_fmac_f32_dpp v30, v14, v118 row_shr:1 row_mask:0xf bank_mask:0xf bound_ctrl:1
	v_fmac_f32_dpp v31, v15, v119 row_shr:1 row_mask:0xf bank_mask:0xf bound_ctrl:1
	v_fmac_f32_dpp v30, v14, v138 row_shr:2 row_mask:0xf bank_mask:0xf bound_ctrl:1
	v_fmac_f32_dpp v31, v15, v139 row_shr:2 row_mask:0xf bank_mask:0xf bound_ctrl:1
	s_cbranch_vccnz .LBB0_407
	ds_read_b128 v[12:15], v152 offset:16
	ds_read_b128 v[56:59], v153 offset:16
	s_waitcnt lgkmcnt(0)
	v_cndmask_b32_e64 v56, v12, v56, s[8:9]
	v_mul_f32_e32 v56, v161, v56
	v_fmac_f32_e32 v56, v157, v12
	v_cndmask_b32_e64 v12, v14, v58, s[8:9]
	v_mul_f32_e32 v12, v162, v12
	v_fmac_f32_e32 v12, v158, v14
	v_cndmask_b32_e64 v57, v13, v57, s[8:9]
	v_add_f32_e32 v30, v30, v12
	v_cndmask_b32_e64 v12, v15, v59, s[8:9]
	v_mul_f32_e32 v57, v163, v57
	v_mul_f32_e32 v12, v160, v12
	v_fmac_f32_e32 v57, v159, v13
	v_fmac_f32_e32 v12, v156, v15
	v_add_f32_e32 v28, v28, v56
	v_add_f32_e32 v29, v29, v57
	v_add_f32_e32 v31, v31, v12

.LBB0_1000:
	s_or_b64 exec, exec, s[8:9]
	s_waitcnt lgkmcnt(0)
	s_barrier
	v_add_u32_e32 v187, s5, v189
	ds_read_b128 v[148:151], v187 offset:9216
	ds_read_b128 v[152:155], v187 offset:8192
	ds_read_b128 v[40:43], v187 offset:10240
	ds_read_b128 v[160:163], v187 offset:11264
	s_add_i32 s4, s5, s79
	s_add_i32 s12, s4, 0xfffffc00
	v_cmp_eq_u32_e64 s[8:9], 0, v210
	v_cmp_gt_u32_e64 s[10:11], 2, v210
	s_waitcnt lgkmcnt(0)
	v_pk_fma_f32 v[6:7], v[166:167], v[42:43], v[162:163]
	v_pk_fma_f32 v[4:5], v[164:165], v[40:41], v[160:161]
	v_add_u32_e32 v191, s12, v189
	s_add_i32 s12, s4, 0xfffff800
	v_fmac_f32_dpp v4, v164, v148 row_shr:1 row_mask:0xf bank_mask:0xf bound_ctrl:1
	v_fmac_f32_dpp v5, v165, v149 row_shr:1 row_mask:0xf bank_mask:0xf bound_ctrl:1
	v_fmac_f32_dpp v4, v164, v152 row_shr:2 row_mask:0xf bank_mask:0xf bound_ctrl:1
	v_fmac_f32_dpp v5, v165, v153 row_shr:2 row_mask:0xf bank_mask:0xf bound_ctrl:1
	v_fmac_f32_dpp v6, v166, v150 row_shr:1 row_mask:0xf bank_mask:0xf bound_ctrl:1
	v_fmac_f32_dpp v7, v167, v151 row_shr:1 row_mask:0xf bank_mask:0xf bound_ctrl:1
	v_fmac_f32_dpp v6, v166, v154 row_shr:2 row_mask:0xf bank_mask:0xf bound_ctrl:1
	v_fmac_f32_dpp v7, v167, v155 row_shr:2 row_mask:0xf bank_mask:0xf bound_ctrl:1
	v_cndmask_b32_e64 v195, 0, v148, s[8:9]
	v_cndmask_b32_e64 v211, 0, v152, s[10:11]
	v_cndmask_b32_e64 v201, 0, v149, s[8:9]
	v_cndmask_b32_e64 v213, 0, v153, s[10:11]
	v_cndmask_b32_e64 v199, 0, v150, s[8:9]
	v_cndmask_b32_e64 v212, 0, v154, s[10:11]
	v_cndmask_b32_e64 v197, 0, v151, s[8:9]
	v_cndmask_b32_e64 v210, 0, v155, s[10:11]
	v_add_u32_e32 v193, s12, v189
	v_fmac_f32_dpp v4, v156, v195 row_ror:1 row_mask:0xf bank_mask:0xf
	v_fmac_f32_dpp v5, v157, v201 row_ror:1 row_mask:0xf bank_mask:0xf
	v_fmac_f32_dpp v4, v156, v211 row_ror:2 row_mask:0xf bank_mask:0xf
	v_fmac_f32_dpp v5, v157, v213 row_ror:2 row_mask:0xf bank_mask:0xf
	v_fmac_f32_dpp v6, v158, v199 row_ror:1 row_mask:0xf bank_mask:0xf
	v_fmac_f32_dpp v7, v159, v197 row_ror:1 row_mask:0xf bank_mask:0xf
	v_fmac_f32_dpp v6, v158, v212 row_ror:2 row_mask:0xf bank_mask:0xf
	v_fmac_f32_dpp v7, v159, v210 row_ror:2 row_mask:0xf bank_mask:0xf
	s_nop 0
	v_pk_fma_f32 v[16:17], v[156:157], v[40:41], v[160:161]
	v_pk_fma_f32 v[18:19], v[158:159], v[42:43], v[162:163]
	v_mov_b32_e32 v0, v17
	s_nop 0
	v_fmac_f32_dpp v16, v156, v148 row_shr:1 row_mask:0xf bank_mask:0xf bound_ctrl:1
	v_fmac_f32_dpp v0, v157, v149 row_shr:1 row_mask:0xf bank_mask:0xf bound_ctrl:1
	v_fmac_f32_dpp v16, v156, v152 row_shr:2 row_mask:0xf bank_mask:0xf bound_ctrl:1
	v_fmac_f32_dpp v0, v157, v153 row_shr:2 row_mask:0xf bank_mask:0xf bound_ctrl:1
	v_fmac_f32_dpp v18, v158, v150 row_shr:1 row_mask:0xf bank_mask:0xf bound_ctrl:1
	v_fmac_f32_dpp v19, v159, v151 row_shr:1 row_mask:0xf bank_mask:0xf bound_ctrl:1
	v_fmac_f32_dpp v18, v158, v154 row_shr:2 row_mask:0xf bank_mask:0xf bound_ctrl:1
	v_fmac_f32_dpp v19, v159, v155 row_shr:2 row_mask:0xf bank_mask:0xf bound_ctrl:1
	s_nop 0
	v_fmac_f32_dpp v16, v144, v195 row_ror:1 row_mask:0xf bank_mask:0xf
	v_fmac_f32_dpp v0, v145, v201 row_ror:1 row_mask:0xf bank_mask:0xf
	v_fmac_f32_dpp v16, v144, v211 row_ror:2 row_mask:0xf bank_mask:0xf
	v_fmac_f32_dpp v0, v145, v213 row_ror:2 row_mask:0xf bank_mask:0xf
	v_fmac_f32_dpp v18, v146, v199 row_ror:1 row_mask:0xf bank_mask:0xf
	v_fmac_f32_dpp v19, v147, v197 row_ror:1 row_mask:0xf bank_mask:0xf
	v_fmac_f32_dpp v18, v146, v212 row_ror:2 row_mask:0xf bank_mask:0xf
	v_fmac_f32_dpp v19, v147, v210 row_ror:2 row_mask:0xf bank_mask:0xf
	s_nop 0
	v_mov_b32_e32 v17, v0
	v_pk_fma_f32 v[34:35], v[146:147], v[42:43], v[162:163]
	v_pk_fma_f32 v[32:33], v[144:145], v[40:41], v[160:161]
	v_mov_b32_e32 v0, v35
	s_nop 0
	v_fmac_f32_dpp v32, v144, v148 row_shr:1 row_mask:0xf bank_mask:0xf bound_ctrl:1
	v_fmac_f32_dpp v33, v145, v149 row_shr:1 row_mask:0xf bank_mask:0xf bound_ctrl:1
	v_fmac_f32_dpp v32, v144, v152 row_shr:2 row_mask:0xf bank_mask:0xf bound_ctrl:1
	v_fmac_f32_dpp v33, v145, v153 row_shr:2 row_mask:0xf bank_mask:0xf bound_ctrl:1
	v_fmac_f32_dpp v34, v146, v150 row_shr:1 row_mask:0xf bank_mask:0xf bound_ctrl:1
	v_fmac_f32_dpp v0, v147, v151 row_shr:1 row_mask:0xf bank_mask:0xf bound_ctrl:1
	v_fmac_f32_dpp v34, v146, v154 row_shr:2 row_mask:0xf bank_mask:0xf bound_ctrl:1
	v_fmac_f32_dpp v0, v147, v155 row_shr:2 row_mask:0xf bank_mask:0xf bound_ctrl:1
	s_nop 0
	v_fmac_f32_dpp v32, v140, v195 row_ror:1 row_mask:0xf bank_mask:0xf
	v_fmac_f32_dpp v33, v141, v201 row_ror:1 row_mask:0xf bank_mask:0xf
	v_fmac_f32_dpp v32, v140, v211 row_ror:2 row_mask:0xf bank_mask:0xf
	v_fmac_f32_dpp v33, v141, v213 row_ror:2 row_mask:0xf bank_mask:0xf
	v_fmac_f32_dpp v34, v142, v199 row_ror:1 row_mask:0xf bank_mask:0xf
	v_fmac_f32_dpp v0, v143, v197 row_ror:1 row_mask:0xf bank_mask:0xf
	v_fmac_f32_dpp v34, v142, v212 row_ror:2 row_mask:0xf bank_mask:0xf
	v_fmac_f32_dpp v0, v143, v210 row_ror:2 row_mask:0xf bank_mask:0xf
	s_nop 0
	v_mov_b32_e32 v35, v0
	v_pk_fma_f32 v[0:1], v[142:143], v[42:43], v[162:163]
	v_pk_fma_f32 v[2:3], v[140:141], v[40:41], v[160:161]
	v_mov_b32_e32 v62, v0
	v_mov_b32_e32 v60, v2
	v_cndmask_b32_e64 v0, 0, 1, s[34:35]
	s_nop 0
	v_fmac_f32_dpp v60, v140, v148 row_shr:1 row_mask:0xf bank_mask:0xf bound_ctrl:1
	v_fmac_f32_dpp v3, v141, v149 row_shr:1 row_mask:0xf bank_mask:0xf bound_ctrl:1
	v_fmac_f32_dpp v60, v140, v152 row_shr:2 row_mask:0xf bank_mask:0xf bound_ctrl:1
	v_fmac_f32_dpp v3, v141, v153 row_shr:2 row_mask:0xf bank_mask:0xf bound_ctrl:1
	v_fmac_f32_dpp v62, v142, v150 row_shr:1 row_mask:0xf bank_mask:0xf bound_ctrl:1
	v_fmac_f32_dpp v1, v143, v151 row_shr:1 row_mask:0xf bank_mask:0xf bound_ctrl:1
	v_fmac_f32_dpp v62, v142, v154 row_shr:2 row_mask:0xf bank_mask:0xf bound_ctrl:1
	v_fmac_f32_dpp v1, v143, v155 row_shr:2 row_mask:0xf bank_mask:0xf bound_ctrl:1
	v_cmp_ne_u32_e64 s[12:13], 1, v0
	v_mov_b32_e32 v61, v3
	s_andn2_b64 vcc, exec, s[34:35]
	v_mov_b32_e32 v63, v1
	s_cbranch_vccnz .LBB0_1002
	ds_read_b128 v[8:11], v191
	ds_read_b128 v[140:143], v193
	s_waitcnt lgkmcnt(0)
	v_cndmask_b32_e64 v0, v8, v140, s[8:9]
	v_mul_f32_e32 v0, v211, v0
	v_fmac_f32_e32 v0, v195, v8
	v_add_f32_e32 v60, v60, v0
	v_cndmask_b32_e64 v0, v10, v142, s[8:9]
	v_mul_f32_e32 v0, v212, v0
	v_fmac_f32_e32 v0, v199, v10
	v_cndmask_b32_e64 v2, v9, v141, s[8:9]
	v_add_f32_e32 v62, v62, v0
	v_cndmask_b32_e64 v0, v11, v143, s[8:9]
	v_mul_f32_e32 v2, v213, v2
	v_mul_f32_e32 v0, v210, v0
	v_fmac_f32_e32 v2, v201, v9
	v_fmac_f32_e32 v0, v197, v11
	v_add_f32_e32 v61, v3, v2
	v_add_f32_e32 v63, v1, v0
.LBB0_1002:
	s_add_i32 s5, s5, s80
	s_add_i32 s14, s5, 0xfffffc00
	v_pk_fma_f32 v[2:3], v[22:23], v[42:43], v[162:163]
	v_pk_fma_f32 v[0:1], v[20:21], v[40:41], v[160:161]
	v_add_u32_e32 v156, s14, v189
	s_add_i32 s14, s5, 0xfffff800
	v_fmac_f32_dpp v0, v20, v148 row_shr:1 row_mask:0xf bank_mask:0xf bound_ctrl:1
	v_fmac_f32_dpp v1, v21, v149 row_shr:1 row_mask:0xf bank_mask:0xf bound_ctrl:1
	v_fmac_f32_dpp v0, v20, v152 row_shr:2 row_mask:0xf bank_mask:0xf bound_ctrl:1
	v_fmac_f32_dpp v1, v21, v153 row_shr:2 row_mask:0xf bank_mask:0xf bound_ctrl:1
	v_fmac_f32_dpp v2, v22, v150 row_shr:1 row_mask:0xf bank_mask:0xf bound_ctrl:1
	v_fmac_f32_dpp v3, v23, v151 row_shr:1 row_mask:0xf bank_mask:0xf bound_ctrl:1
	v_fmac_f32_dpp v2, v22, v154 row_shr:2 row_mask:0xf bank_mask:0xf bound_ctrl:1
	v_fmac_f32_dpp v3, v23, v155 row_shr:2 row_mask:0xf bank_mask:0xf bound_ctrl:1
	v_add_u32_e32 v157, s14, v189
	v_fmac_f32_dpp v0, v48, v195 row_ror:1 row_mask:0xf bank_mask:0xf
	v_fmac_f32_dpp v1, v49, v201 row_ror:1 row_mask:0xf bank_mask:0xf
	v_fmac_f32_dpp v0, v48, v211 row_ror:2 row_mask:0xf bank_mask:0xf
	v_fmac_f32_dpp v1, v49, v213 row_ror:2 row_mask:0xf bank_mask:0xf
	v_fmac_f32_dpp v2, v50, v199 row_ror:1 row_mask:0xf bank_mask:0xf
	v_fmac_f32_dpp v3, v51, v197 row_ror:1 row_mask:0xf bank_mask:0xf
	v_fmac_f32_dpp v2, v50, v212 row_ror:2 row_mask:0xf bank_mask:0xf
	v_fmac_f32_dpp v3, v51, v210 row_ror:2 row_mask:0xf bank_mask:0xf
	s_nop 0
	v_pk_fma_f32 v[10:11], v[50:51], v[42:43], v[162:163]
	v_pk_fma_f32 v[8:9], v[48:49], v[40:41], v[160:161]
	s_nop 0
	s_nop 0
	v_fmac_f32_dpp v8, v48, v148 row_shr:1 row_mask:0xf bank_mask:0xf bound_ctrl:1
	v_fmac_f32_dpp v9, v49, v149 row_shr:1 row_mask:0xf bank_mask:0xf bound_ctrl:1
	v_fmac_f32_dpp v8, v48, v152 row_shr:2 row_mask:0xf bank_mask:0xf bound_ctrl:1
	v_fmac_f32_dpp v9, v49, v153 row_shr:2 row_mask:0xf bank_mask:0xf bound_ctrl:1
	v_fmac_f32_dpp v10, v50, v150 row_shr:1 row_mask:0xf bank_mask:0xf bound_ctrl:1
	v_fmac_f32_dpp v11, v51, v151 row_shr:1 row_mask:0xf bank_mask:0xf bound_ctrl:1
	v_fmac_f32_dpp v10, v50, v154 row_shr:2 row_mask:0xf bank_mask:0xf bound_ctrl:1
	v_fmac_f32_dpp v11, v51, v155 row_shr:2 row_mask:0xf bank_mask:0xf bound_ctrl:1
	s_nop 0
	v_fmac_f32_dpp v8, v68, v195 row_ror:1 row_mask:0xf bank_mask:0xf
	v_fmac_f32_dpp v9, v69, v201 row_ror:1 row_mask:0xf bank_mask:0xf
	v_fmac_f32_dpp v8, v68, v211 row_ror:2 row_mask:0xf bank_mask:0xf
	v_fmac_f32_dpp v9, v69, v213 row_ror:2 row_mask:0xf bank_mask:0xf
	v_fmac_f32_dpp v10, v70, v199 row_ror:1 row_mask:0xf bank_mask:0xf
	v_fmac_f32_dpp v11, v71, v197 row_ror:1 row_mask:0xf bank_mask:0xf
	v_fmac_f32_dpp v10, v70, v212 row_ror:2 row_mask:0xf bank_mask:0xf
	v_fmac_f32_dpp v11, v71, v210 row_ror:2 row_mask:0xf bank_mask:0xf
	s_nop 0
	v_pk_fma_f32 v[22:23], v[70:71], v[42:43], v[162:163]
	v_pk_fma_f32 v[20:21], v[68:69], v[40:41], v[160:161]
	s_nop 0
	s_nop 0
	v_fmac_f32_dpp v20, v68, v148 row_shr:1 row_mask:0xf bank_mask:0xf bound_ctrl:1
	v_fmac_f32_dpp v21, v69, v149 row_shr:1 row_mask:0xf bank_mask:0xf bound_ctrl:1
	v_fmac_f32_dpp v20, v68, v152 row_shr:2 row_mask:0xf bank_mask:0xf bound_ctrl:1
	v_fmac_f32_dpp v21, v69, v153 row_shr:2 row_mask:0xf bank_mask:0xf bound_ctrl:1
	v_fmac_f32_dpp v22, v70, v150 row_shr:1 row_mask:0xf bank_mask:0xf bound_ctrl:1
	v_fmac_f32_dpp v23, v71, v151 row_shr:1 row_mask:0xf bank_mask:0xf bound_ctrl:1
	v_fmac_f32_dpp v22, v70, v154 row_shr:2 row_mask:0xf bank_mask:0xf bound_ctrl:1
	v_fmac_f32_dpp v23, v71, v155 row_shr:2 row_mask:0xf bank_mask:0xf bound_ctrl:1
	s_nop 0
	v_fmac_f32_dpp v20, v80, v195 row_ror:1 row_mask:0xf bank_mask:0xf
	v_fmac_f32_dpp v21, v81, v201 row_ror:1 row_mask:0xf bank_mask:0xf
	v_fmac_f32_dpp v20, v80, v211 row_ror:2 row_mask:0xf bank_mask:0xf
	v_fmac_f32_dpp v21, v81, v213 row_ror:2 row_mask:0xf bank_mask:0xf
	v_fmac_f32_dpp v22, v82, v199 row_ror:1 row_mask:0xf bank_mask:0xf
	v_fmac_f32_dpp v23, v83, v197 row_ror:1 row_mask:0xf bank_mask:0xf
	v_fmac_f32_dpp v22, v82, v212 row_ror:2 row_mask:0xf bank_mask:0xf
	v_fmac_f32_dpp v23, v83, v210 row_ror:2 row_mask:0xf bank_mask:0xf
	s_nop 0
	v_cndmask_b32_e64 v48, 0, 1, s[36:37]
	v_pk_fma_f32 v[42:43], v[82:83], v[42:43], v[162:163]
	v_pk_fma_f32 v[40:41], v[80:81], v[40:41], v[160:161]
	v_cmp_ne_u32_e64 s[14:15], 1, v48
	s_andn2_b64 vcc, exec, s[36:37]
	s_nop 1
	v_fmac_f32_dpp v40, v80, v148 row_shr:1 row_mask:0xf bank_mask:0xf bound_ctrl:1
	v_fmac_f32_dpp v41, v81, v149 row_shr:1 row_mask:0xf bank_mask:0xf bound_ctrl:1
	v_fmac_f32_dpp v40, v80, v152 row_shr:2 row_mask:0xf bank_mask:0xf bound_ctrl:1
	v_fmac_f32_dpp v41, v81, v153 row_shr:2 row_mask:0xf bank_mask:0xf bound_ctrl:1
	v_fmac_f32_dpp v42, v82, v150 row_shr:1 row_mask:0xf bank_mask:0xf bound_ctrl:1
	v_fmac_f32_dpp v43, v83, v151 row_shr:1 row_mask:0xf bank_mask:0xf bound_ctrl:1
	v_fmac_f32_dpp v42, v82, v154 row_shr:2 row_mask:0xf bank_mask:0xf bound_ctrl:1
	v_fmac_f32_dpp v43, v83, v155 row_shr:2 row_mask:0xf bank_mask:0xf bound_ctrl:1
	s_cbranch_vccnz .LBB0_1004
	ds_read_b128 v[48:51], v156
	ds_read_b128 v[68:71], v157
	s_waitcnt lgkmcnt(0)
	v_cndmask_b32_e64 v68, v48, v68, s[8:9]
	v_mul_f32_e32 v68, v211, v68
	v_fmac_f32_e32 v68, v195, v48
	v_cndmask_b32_e64 v48, v50, v70, s[8:9]
	v_mul_f32_e32 v48, v212, v48
	v_fmac_f32_e32 v48, v199, v50
	v_cndmask_b32_e64 v69, v49, v69, s[8:9]
	v_add_f32_e32 v42, v42, v48
	v_cndmask_b32_e64 v48, v51, v71, s[8:9]
	v_mul_f32_e32 v69, v213, v69
	v_mul_f32_e32 v48, v210, v48
	v_fmac_f32_e32 v69, v201, v49
	v_fmac_f32_e32 v48, v197, v51
	v_add_f32_e32 v40, v40, v68
	v_add_f32_e32 v41, v41, v69
	v_add_f32_e32 v43, v43, v48
.LBB0_1004:
	ds_read_b128 v[140:143], v187 offset:9232
	ds_read_b128 v[144:147], v187 offset:8208
	ds_read_b128 v[148:151], v187 offset:10256
	ds_read_b128 v[152:155], v187 offset:11280
	s_waitcnt lgkmcnt(3)
	v_cndmask_b32_e64 v159, 0, v140, s[8:9]
	s_waitcnt lgkmcnt(2)
	v_cndmask_b32_e64 v163, 0, v144, s[10:11]
	v_cndmask_b32_e64 v161, 0, v141, s[8:9]
	s_waitcnt lgkmcnt(0)
	v_pk_fma_f32 v[70:71], v[98:99], v[150:151], v[154:155]
	v_pk_fma_f32 v[68:69], v[96:97], v[148:149], v[152:153]
	v_cndmask_b32_e64 v165, 0, v145, s[10:11]
	s_nop 0
	v_fmac_f32_dpp v68, v96, v140 row_shr:1 row_mask:0xf bank_mask:0xf bound_ctrl:1
	v_fmac_f32_dpp v69, v97, v141 row_shr:1 row_mask:0xf bank_mask:0xf bound_ctrl:1
	v_fmac_f32_dpp v68, v96, v144 row_shr:2 row_mask:0xf bank_mask:0xf bound_ctrl:1
	v_fmac_f32_dpp v69, v97, v145 row_shr:2 row_mask:0xf bank_mask:0xf bound_ctrl:1
	v_fmac_f32_dpp v70, v98, v142 row_shr:1 row_mask:0xf bank_mask:0xf bound_ctrl:1
	v_fmac_f32_dpp v71, v99, v143 row_shr:1 row_mask:0xf bank_mask:0xf bound_ctrl:1
	v_fmac_f32_dpp v70, v98, v146 row_shr:2 row_mask:0xf bank_mask:0xf bound_ctrl:1
	v_fmac_f32_dpp v71, v99, v147 row_shr:2 row_mask:0xf bank_mask:0xf bound_ctrl:1
	v_cndmask_b32_e64 v160, 0, v142, s[8:9]
	v_cndmask_b32_e64 v164, 0, v146, s[10:11]
	v_cndmask_b32_e64 v158, 0, v143, s[8:9]
	v_cndmask_b32_e64 v162, 0, v147, s[10:11]
	v_fmac_f32_dpp v68, v136, v159 row_ror:1 row_mask:0xf bank_mask:0xf
	v_fmac_f32_dpp v69, v137, v161 row_ror:1 row_mask:0xf bank_mask:0xf
	v_fmac_f32_dpp v68, v136, v163 row_ror:2 row_mask:0xf bank_mask:0xf
	v_fmac_f32_dpp v69, v137, v165 row_ror:2 row_mask:0xf bank_mask:0xf
	v_fmac_f32_dpp v70, v138, v160 row_ror:1 row_mask:0xf bank_mask:0xf
	v_fmac_f32_dpp v71, v139, v158 row_ror:1 row_mask:0xf bank_mask:0xf
	v_fmac_f32_dpp v70, v138, v164 row_ror:2 row_mask:0xf bank_mask:0xf
	v_fmac_f32_dpp v71, v139, v162 row_ror:2 row_mask:0xf bank_mask:0xf
	s_nop 0
	v_pk_fma_f32 v[82:83], v[138:139], v[150:151], v[154:155]
	v_pk_fma_f32 v[80:81], v[136:137], v[148:149], v[152:153]
	v_mov_b32_e32 v49, v83
	v_mov_b32_e32 v48, v81
	s_nop 0
	v_fmac_f32_dpp v80, v136, v140 row_shr:1 row_mask:0xf bank_mask:0xf bound_ctrl:1
	v_fmac_f32_dpp v48, v137, v141 row_shr:1 row_mask:0xf bank_mask:0xf bound_ctrl:1
	v_fmac_f32_dpp v80, v136, v144 row_shr:2 row_mask:0xf bank_mask:0xf bound_ctrl:1
	v_fmac_f32_dpp v48, v137, v145 row_shr:2 row_mask:0xf bank_mask:0xf bound_ctrl:1
	v_fmac_f32_dpp v82, v138, v142 row_shr:1 row_mask:0xf bank_mask:0xf bound_ctrl:1
	v_fmac_f32_dpp v49, v139, v143 row_shr:1 row_mask:0xf bank_mask:0xf bound_ctrl:1
	v_fmac_f32_dpp v82, v138, v146 row_shr:2 row_mask:0xf bank_mask:0xf bound_ctrl:1
	v_fmac_f32_dpp v49, v139, v147 row_shr:2 row_mask:0xf bank_mask:0xf bound_ctrl:1
	s_nop 0
	v_fmac_f32_dpp v80, v120, v159 row_ror:1 row_mask:0xf bank_mask:0xf
	v_fmac_f32_dpp v48, v121, v161 row_ror:1 row_mask:0xf bank_mask:0xf
	v_fmac_f32_dpp v80, v120, v163 row_ror:2 row_mask:0xf bank_mask:0xf
	v_fmac_f32_dpp v48, v121, v165 row_ror:2 row_mask:0xf bank_mask:0xf
	v_fmac_f32_dpp v82, v122, v160 row_ror:1 row_mask:0xf bank_mask:0xf
	v_fmac_f32_dpp v49, v123, v158 row_ror:1 row_mask:0xf bank_mask:0xf
	v_fmac_f32_dpp v82, v122, v164 row_ror:2 row_mask:0xf bank_mask:0xf
	v_fmac_f32_dpp v49, v123, v162 row_ror:2 row_mask:0xf bank_mask:0xf
	s_nop 0
	v_mov_b32_e32 v81, v48
	v_mov_b32_e32 v83, v49
	v_pk_fma_f32 v[98:99], v[122:123], v[150:151], v[154:155]
	v_pk_fma_f32 v[96:97], v[120:121], v[148:149], v[152:153]
	v_mov_b32_e32 v48, v99
	s_nop 0
	v_fmac_f32_dpp v96, v120, v140 row_shr:1 row_mask:0xf bank_mask:0xf bound_ctrl:1
	v_fmac_f32_dpp v97, v121, v141 row_shr:1 row_mask:0xf bank_mask:0xf bound_ctrl:1
	v_fmac_f32_dpp v96, v120, v144 row_shr:2 row_mask:0xf bank_mask:0xf bound_ctrl:1
	v_fmac_f32_dpp v97, v121, v145 row_shr:2 row_mask:0xf bank_mask:0xf bound_ctrl:1
	v_fmac_f32_dpp v98, v122, v142 row_shr:1 row_mask:0xf bank_mask:0xf bound_ctrl:1
	v_fmac_f32_dpp v48, v123, v143 row_shr:1 row_mask:0xf bank_mask:0xf bound_ctrl:1
	v_fmac_f32_dpp v98, v122, v146 row_shr:2 row_mask:0xf bank_mask:0xf bound_ctrl:1
	v_fmac_f32_dpp v48, v123, v147 row_shr:2 row_mask:0xf bank_mask:0xf bound_ctrl:1
	s_nop 0
	v_fmac_f32_dpp v96, v132, v159 row_ror:1 row_mask:0xf bank_mask:0xf
	v_fmac_f32_dpp v97, v133, v161 row_ror:1 row_mask:0xf bank_mask:0xf
	v_fmac_f32_dpp v96, v132, v163 row_ror:2 row_mask:0xf bank_mask:0xf
	v_fmac_f32_dpp v97, v133, v165 row_ror:2 row_mask:0xf bank_mask:0xf
	v_fmac_f32_dpp v98, v134, v160 row_ror:1 row_mask:0xf bank_mask:0xf
	v_fmac_f32_dpp v48, v135, v158 row_ror:1 row_mask:0xf bank_mask:0xf
	v_fmac_f32_dpp v98, v134, v164 row_ror:2 row_mask:0xf bank_mask:0xf
	v_fmac_f32_dpp v48, v135, v162 row_ror:2 row_mask:0xf bank_mask:0xf
	s_nop 0
	v_mov_b32_e32 v99, v48
	v_pk_fma_f32 v[48:49], v[134:135], v[150:151], v[154:155]
	v_pk_fma_f32 v[50:51], v[132:133], v[148:149], v[152:153]
	v_mov_b32_e32 v122, v48
	v_mov_b32_e32 v120, v50
	s_nop 1
	v_fmac_f32_dpp v120, v132, v140 row_shr:1 row_mask:0xf bank_mask:0xf bound_ctrl:1
	v_fmac_f32_dpp v51, v133, v141 row_shr:1 row_mask:0xf bank_mask:0xf bound_ctrl:1
	v_fmac_f32_dpp v120, v132, v144 row_shr:2 row_mask:0xf bank_mask:0xf bound_ctrl:1
	v_fmac_f32_dpp v51, v133, v145 row_shr:2 row_mask:0xf bank_mask:0xf bound_ctrl:1
	v_fmac_f32_dpp v122, v134, v142 row_shr:1 row_mask:0xf bank_mask:0xf bound_ctrl:1
	v_fmac_f32_dpp v49, v135, v143 row_shr:1 row_mask:0xf bank_mask:0xf bound_ctrl:1
	v_fmac_f32_dpp v122, v134, v146 row_shr:2 row_mask:0xf bank_mask:0xf bound_ctrl:1
	v_fmac_f32_dpp v49, v135, v147 row_shr:2 row_mask:0xf bank_mask:0xf bound_ctrl:1
	s_and_b64 vcc, exec, s[12:13]
	v_mov_b32_e32 v121, v51
	v_mov_b32_e32 v123, v49
	s_cbranch_vccnz .LBB0_1006
	ds_read_b128 v[132:135], v191 offset:16
	ds_read_b128 v[136:139], v193 offset:16
	s_waitcnt lgkmcnt(0)
	v_cndmask_b32_e64 v48, v132, v136, s[8:9]
	v_mul_f32_e32 v48, v163, v48
	v_fmac_f32_e32 v48, v159, v132
	v_add_f32_e32 v120, v120, v48
	v_cndmask_b32_e64 v48, v134, v138, s[8:9]
	v_mul_f32_e32 v48, v164, v48
	v_fmac_f32_e32 v48, v160, v134
	v_cndmask_b32_e64 v50, v133, v137, s[8:9]
	v_add_f32_e32 v122, v122, v48
	v_cndmask_b32_e64 v48, v135, v139, s[8:9]
	v_mul_f32_e32 v50, v165, v50
	v_mul_f32_e32 v48, v162, v48
	v_fmac_f32_e32 v50, v161, v133
	v_fmac_f32_e32 v48, v158, v135
	v_add_f32_e32 v121, v51, v50
	v_add_f32_e32 v123, v49, v48

.LBB0_1008:
	ds_read_b128 v[136:139], v187 offset:9728
	ds_read_b128 v[140:143], v187 offset:8704
	ds_read_b128 v[144:147], v187 offset:10752
	ds_read_b128 v[148:151], v187 offset:11776
	s_add_i32 s46, s4, 0xfffffe00
	s_addk_i32 s4, 0xfa00
	s_waitcnt lgkmcnt(3)
	v_cndmask_b32_e64 v157, 0, v136, s[8:9]
	s_waitcnt lgkmcnt(2)
	v_cndmask_b32_e64 v161, 0, v140, s[10:11]
	s_waitcnt lgkmcnt(0)
	v_pk_fma_f32 v[130:131], v[126:127], v[146:147], v[150:151]
	v_pk_fma_f32 v[128:129], v[124:125], v[144:145], v[148:149]
	v_cndmask_b32_e64 v159, 0, v137, s[8:9]
	s_nop 0
	v_fmac_f32_dpp v128, v124, v136 row_shr:1 row_mask:0xf bank_mask:0xf bound_ctrl:1
	v_fmac_f32_dpp v129, v125, v137 row_shr:1 row_mask:0xf bank_mask:0xf bound_ctrl:1
	v_fmac_f32_dpp v128, v124, v140 row_shr:2 row_mask:0xf bank_mask:0xf bound_ctrl:1
	v_fmac_f32_dpp v129, v125, v141 row_shr:2 row_mask:0xf bank_mask:0xf bound_ctrl:1
	v_fmac_f32_dpp v130, v126, v138 row_shr:1 row_mask:0xf bank_mask:0xf bound_ctrl:1
	v_fmac_f32_dpp v131, v127, v139 row_shr:1 row_mask:0xf bank_mask:0xf bound_ctrl:1
	v_fmac_f32_dpp v130, v126, v142 row_shr:2 row_mask:0xf bank_mask:0xf bound_ctrl:1
	v_fmac_f32_dpp v131, v127, v143 row_shr:2 row_mask:0xf bank_mask:0xf bound_ctrl:1
	v_cndmask_b32_e64 v163, 0, v141, s[10:11]
	v_cndmask_b32_e64 v158, 0, v138, s[8:9]
	v_cndmask_b32_e64 v162, 0, v142, s[10:11]
	v_cndmask_b32_e64 v156, 0, v139, s[8:9]
	v_cndmask_b32_e64 v160, 0, v143, s[10:11]
	v_add_u32_e32 v154, s46, v189
	v_add_u32_e32 v155, s4, v189
	v_fmac_f32_dpp v128, v112, v157 row_ror:1 row_mask:0xf bank_mask:0xf
	v_fmac_f32_dpp v129, v113, v159 row_ror:1 row_mask:0xf bank_mask:0xf
	v_fmac_f32_dpp v128, v112, v161 row_ror:2 row_mask:0xf bank_mask:0xf
	v_fmac_f32_dpp v129, v113, v163 row_ror:2 row_mask:0xf bank_mask:0xf
	v_fmac_f32_dpp v130, v114, v158 row_ror:1 row_mask:0xf bank_mask:0xf
	v_fmac_f32_dpp v131, v115, v156 row_ror:1 row_mask:0xf bank_mask:0xf
	v_fmac_f32_dpp v130, v114, v162 row_ror:2 row_mask:0xf bank_mask:0xf
	v_fmac_f32_dpp v131, v115, v160 row_ror:2 row_mask:0xf bank_mask:0xf
	s_nop 0
	v_pk_fma_f32 v[126:127], v[114:115], v[146:147], v[150:151]
	v_pk_fma_f32 v[124:125], v[112:113], v[144:145], v[148:149]
	s_nop 0
	s_nop 0
	v_fmac_f32_dpp v124, v112, v136 row_shr:1 row_mask:0xf bank_mask:0xf bound_ctrl:1
	v_fmac_f32_dpp v125, v113, v137 row_shr:1 row_mask:0xf bank_mask:0xf bound_ctrl:1
	v_fmac_f32_dpp v124, v112, v140 row_shr:2 row_mask:0xf bank_mask:0xf bound_ctrl:1
	v_fmac_f32_dpp v125, v113, v141 row_shr:2 row_mask:0xf bank_mask:0xf bound_ctrl:1
	v_mov_b32_e32 v112, v127
	s_nop 0
	v_fmac_f32_dpp v126, v114, v138 row_shr:1 row_mask:0xf bank_mask:0xf bound_ctrl:1
	v_fmac_f32_dpp v112, v115, v139 row_shr:1 row_mask:0xf bank_mask:0xf bound_ctrl:1
	v_fmac_f32_dpp v126, v114, v142 row_shr:2 row_mask:0xf bank_mask:0xf bound_ctrl:1
	v_fmac_f32_dpp v112, v115, v143 row_shr:2 row_mask:0xf bank_mask:0xf bound_ctrl:1
	v_fmac_f32_dpp v124, v100, v157 row_ror:1 row_mask:0xf bank_mask:0xf
	v_fmac_f32_dpp v125, v101, v159 row_ror:1 row_mask:0xf bank_mask:0xf
	v_fmac_f32_dpp v124, v100, v161 row_ror:2 row_mask:0xf bank_mask:0xf
	v_fmac_f32_dpp v125, v101, v163 row_ror:2 row_mask:0xf bank_mask:0xf
	s_nop 0
	v_fmac_f32_dpp v126, v102, v158 row_ror:1 row_mask:0xf bank_mask:0xf
	v_fmac_f32_dpp v112, v103, v156 row_ror:1 row_mask:0xf bank_mask:0xf
	v_fmac_f32_dpp v126, v102, v162 row_ror:2 row_mask:0xf bank_mask:0xf
	v_fmac_f32_dpp v112, v103, v160 row_ror:2 row_mask:0xf bank_mask:0xf
	s_nop 0
	v_mov_b32_e32 v127, v112
	v_pk_fma_f32 v[114:115], v[102:103], v[146:147], v[150:151]
	v_pk_fma_f32 v[112:113], v[100:101], v[144:145], v[148:149]
	s_nop 0
	s_nop 0
	v_fmac_f32_dpp v112, v100, v136 row_shr:1 row_mask:0xf bank_mask:0xf bound_ctrl:1
	v_fmac_f32_dpp v113, v101, v137 row_shr:1 row_mask:0xf bank_mask:0xf bound_ctrl:1
	v_fmac_f32_dpp v112, v100, v140 row_shr:2 row_mask:0xf bank_mask:0xf bound_ctrl:1
	v_fmac_f32_dpp v113, v101, v141 row_shr:2 row_mask:0xf bank_mask:0xf bound_ctrl:1
	v_mov_b32_e32 v100, v115
	s_nop 0
	v_fmac_f32_dpp v114, v102, v138 row_shr:1 row_mask:0xf bank_mask:0xf bound_ctrl:1
	v_fmac_f32_dpp v100, v103, v139 row_shr:1 row_mask:0xf bank_mask:0xf bound_ctrl:1
	v_fmac_f32_dpp v114, v102, v142 row_shr:2 row_mask:0xf bank_mask:0xf bound_ctrl:1
	v_fmac_f32_dpp v100, v103, v143 row_shr:2 row_mask:0xf bank_mask:0xf bound_ctrl:1
	v_fmac_f32_dpp v112, v88, v157 row_ror:1 row_mask:0xf bank_mask:0xf
	v_fmac_f32_dpp v113, v89, v159 row_ror:1 row_mask:0xf bank_mask:0xf
	v_fmac_f32_dpp v112, v88, v161 row_ror:2 row_mask:0xf bank_mask:0xf
	v_fmac_f32_dpp v113, v89, v163 row_ror:2 row_mask:0xf bank_mask:0xf
	s_nop 0
	v_fmac_f32_dpp v114, v90, v158 row_ror:1 row_mask:0xf bank_mask:0xf
	v_fmac_f32_dpp v100, v91, v156 row_ror:1 row_mask:0xf bank_mask:0xf
	v_fmac_f32_dpp v114, v90, v162 row_ror:2 row_mask:0xf bank_mask:0xf
	v_fmac_f32_dpp v100, v91, v160 row_ror:2 row_mask:0xf bank_mask:0xf
	s_nop 0
	v_mov_b32_e32 v115, v100
	v_pk_fma_f32 v[100:101], v[90:91], v[146:147], v[150:151]
	v_pk_fma_f32 v[102:103], v[88:89], v[144:145], v[148:149]
	v_mov_b32_e32 v134, v100
	v_mov_b32_e32 v132, v102
	s_nop 1
	v_fmac_f32_dpp v132, v88, v136 row_shr:1 row_mask:0xf bank_mask:0xf bound_ctrl:1
	v_fmac_f32_dpp v103, v89, v137 row_shr:1 row_mask:0xf bank_mask:0xf bound_ctrl:1
	v_fmac_f32_dpp v132, v88, v140 row_shr:2 row_mask:0xf bank_mask:0xf bound_ctrl:1
	v_fmac_f32_dpp v103, v89, v141 row_shr:2 row_mask:0xf bank_mask:0xf bound_ctrl:1
	v_fmac_f32_dpp v134, v90, v138 row_shr:1 row_mask:0xf bank_mask:0xf bound_ctrl:1
	v_fmac_f32_dpp v101, v91, v139 row_shr:1 row_mask:0xf bank_mask:0xf bound_ctrl:1
	v_fmac_f32_dpp v134, v90, v142 row_shr:2 row_mask:0xf bank_mask:0xf bound_ctrl:1
	v_fmac_f32_dpp v101, v91, v143 row_shr:2 row_mask:0xf bank_mask:0xf bound_ctrl:1
	s_and_b64 vcc, exec, s[12:13]
	v_mov_b32_e32 v133, v103
	v_mov_b32_e32 v135, v101
	s_cbranch_vccnz .LBB0_1010
	ds_read_b128 v[88:91], v154
	ds_read_b128 v[164:167], v155
	s_waitcnt lgkmcnt(0)
	v_cndmask_b32_e64 v100, v88, v164, s[8:9]
	v_mul_f32_e32 v100, v161, v100
	v_fmac_f32_e32 v100, v157, v88
	v_cndmask_b32_e64 v88, v90, v166, s[8:9]
	v_mul_f32_e32 v88, v162, v88
	v_fmac_f32_e32 v88, v158, v90
	v_cndmask_b32_e64 v102, v89, v165, s[8:9]
	v_add_f32_e32 v134, v134, v88
	v_cndmask_b32_e64 v88, v91, v167, s[8:9]
	v_mul_f32_e32 v102, v163, v102
	v_mul_f32_e32 v88, v160, v88
	v_fmac_f32_e32 v102, v159, v89
	v_fmac_f32_e32 v88, v156, v91
	v_add_f32_e32 v132, v132, v100
	v_add_f32_e32 v133, v103, v102
	v_add_f32_e32 v135, v101, v88

.LBB0_1015:
	v_pk_fma_f32 v[26:27], v[58:59], v[142:143], v[146:147]
	v_pk_fma_f32 v[24:25], v[56:57], v[140:141], v[144:145]
	s_nop 0
	s_nop 0
	v_fmac_f32_dpp v24, v56, v116 row_shr:1 row_mask:0xf bank_mask:0xf bound_ctrl:1
	v_fmac_f32_dpp v25, v57, v117 row_shr:1 row_mask:0xf bank_mask:0xf bound_ctrl:1
	v_fmac_f32_dpp v24, v56, v136 row_shr:2 row_mask:0xf bank_mask:0xf bound_ctrl:1
	v_fmac_f32_dpp v25, v57, v137 row_shr:2 row_mask:0xf bank_mask:0xf bound_ctrl:1
	v_fmac_f32_dpp v26, v58, v118 row_shr:1 row_mask:0xf bank_mask:0xf bound_ctrl:1
	v_fmac_f32_dpp v27, v59, v119 row_shr:1 row_mask:0xf bank_mask:0xf bound_ctrl:1
	v_fmac_f32_dpp v26, v58, v138 row_shr:2 row_mask:0xf bank_mask:0xf bound_ctrl:1
	v_fmac_f32_dpp v27, v59, v139 row_shr:2 row_mask:0xf bank_mask:0xf bound_ctrl:1
	s_nop 0
	v_fmac_f32_dpp v24, v44, v157 row_ror:1 row_mask:0xf bank_mask:0xf
	v_fmac_f32_dpp v25, v45, v159 row_ror:1 row_mask:0xf bank_mask:0xf
	v_fmac_f32_dpp v24, v44, v161 row_ror:2 row_mask:0xf bank_mask:0xf
	v_fmac_f32_dpp v25, v45, v163 row_ror:2 row_mask:0xf bank_mask:0xf
	v_fmac_f32_dpp v26, v46, v158 row_ror:1 row_mask:0xf bank_mask:0xf
	v_fmac_f32_dpp v27, v47, v156 row_ror:1 row_mask:0xf bank_mask:0xf
	v_fmac_f32_dpp v26, v46, v162 row_ror:2 row_mask:0xf bank_mask:0xf
	v_fmac_f32_dpp v27, v47, v160 row_ror:2 row_mask:0xf bank_mask:0xf
	s_nop 0
	v_pk_fma_f32 v[38:39], v[46:47], v[142:143], v[146:147]
	v_pk_fma_f32 v[36:37], v[44:45], v[140:141], v[144:145]
	s_nop 0
	s_nop 0
	v_fmac_f32_dpp v36, v44, v116 row_shr:1 row_mask:0xf bank_mask:0xf bound_ctrl:1
	v_fmac_f32_dpp v37, v45, v117 row_shr:1 row_mask:0xf bank_mask:0xf bound_ctrl:1
	v_fmac_f32_dpp v36, v44, v136 row_shr:2 row_mask:0xf bank_mask:0xf bound_ctrl:1
	v_fmac_f32_dpp v37, v45, v137 row_shr:2 row_mask:0xf bank_mask:0xf bound_ctrl:1
	v_fmac_f32_dpp v38, v46, v118 row_shr:1 row_mask:0xf bank_mask:0xf bound_ctrl:1
	v_fmac_f32_dpp v39, v47, v119 row_shr:1 row_mask:0xf bank_mask:0xf bound_ctrl:1
	v_fmac_f32_dpp v38, v46, v138 row_shr:2 row_mask:0xf bank_mask:0xf bound_ctrl:1
	v_fmac_f32_dpp v39, v47, v139 row_shr:2 row_mask:0xf bank_mask:0xf bound_ctrl:1
	s_nop 0
	v_fmac_f32_dpp v36, v28, v157 row_ror:1 row_mask:0xf bank_mask:0xf
	v_fmac_f32_dpp v37, v29, v159 row_ror:1 row_mask:0xf bank_mask:0xf
	v_fmac_f32_dpp v36, v28, v161 row_ror:2 row_mask:0xf bank_mask:0xf
	v_fmac_f32_dpp v37, v29, v163 row_ror:2 row_mask:0xf bank_mask:0xf
	v_fmac_f32_dpp v38, v30, v158 row_ror:1 row_mask:0xf bank_mask:0xf
	v_fmac_f32_dpp v39, v31, v156 row_ror:1 row_mask:0xf bank_mask:0xf
	v_fmac_f32_dpp v38, v30, v162 row_ror:2 row_mask:0xf bank_mask:0xf
	v_fmac_f32_dpp v39, v31, v160 row_ror:2 row_mask:0xf bank_mask:0xf
	s_nop 0
	v_pk_fma_f32 v[46:47], v[30:31], v[142:143], v[146:147]
	v_pk_fma_f32 v[44:45], v[28:29], v[140:141], v[144:145]
	s_nop 0
	s_nop 0
	v_fmac_f32_dpp v44, v28, v116 row_shr:1 row_mask:0xf bank_mask:0xf bound_ctrl:1
	v_fmac_f32_dpp v45, v29, v117 row_shr:1 row_mask:0xf bank_mask:0xf bound_ctrl:1
	v_fmac_f32_dpp v44, v28, v136 row_shr:2 row_mask:0xf bank_mask:0xf bound_ctrl:1
	v_fmac_f32_dpp v45, v29, v137 row_shr:2 row_mask:0xf bank_mask:0xf bound_ctrl:1
	v_mov_b32_e32 v28, v47
	s_nop 0
	v_fmac_f32_dpp v46, v30, v118 row_shr:1 row_mask:0xf bank_mask:0xf bound_ctrl:1
	v_fmac_f32_dpp v28, v31, v119 row_shr:1 row_mask:0xf bank_mask:0xf bound_ctrl:1
	v_fmac_f32_dpp v46, v30, v138 row_shr:2 row_mask:0xf bank_mask:0xf bound_ctrl:1
	v_fmac_f32_dpp v28, v31, v139 row_shr:2 row_mask:0xf bank_mask:0xf bound_ctrl:1
	v_fmac_f32_dpp v44, v12, v157 row_ror:1 row_mask:0xf bank_mask:0xf
	v_fmac_f32_dpp v45, v13, v159 row_ror:1 row_mask:0xf bank_mask:0xf
	v_fmac_f32_dpp v44, v12, v161 row_ror:2 row_mask:0xf bank_mask:0xf
	v_fmac_f32_dpp v45, v13, v163 row_ror:2 row_mask:0xf bank_mask:0xf
	s_nop 0
	v_fmac_f32_dpp v46, v14, v158 row_ror:1 row_mask:0xf bank_mask:0xf
	v_fmac_f32_dpp v28, v15, v156 row_ror:1 row_mask:0xf bank_mask:0xf
	v_fmac_f32_dpp v46, v14, v162 row_ror:2 row_mask:0xf bank_mask:0xf
	v_fmac_f32_dpp v28, v15, v160 row_ror:2 row_mask:0xf bank_mask:0xf
	s_nop 0
	v_mov_b32_e32 v47, v28
	v_pk_fma_f32 v[30:31], v[14:15], v[142:143], v[146:147]
	v_pk_fma_f32 v[28:29], v[12:13], v[140:141], v[144:145]
	s_and_b64 vcc, exec, s[14:15]
	s_nop 1
	v_fmac_f32_dpp v28, v12, v116 row_shr:1 row_mask:0xf bank_mask:0xf bound_ctrl:1
	v_fmac_f32_dpp v29, v13, v117 row_shr:1 row_mask:0xf bank_mask:0xf bound_ctrl:1
	v_fmac_f32_dpp v28, v12, v136 row_shr:2 row_mask:0xf bank_mask:0xf bound_ctrl:1
	v_fmac_f32_dpp v29, v13, v137 row_shr:2 row_mask:0xf bank_mask:0xf bound_ctrl:1
	v_fmac_f32_dpp v30, v14, v118 row_shr:1 row_mask:0xf bank_mask:0xf bound_ctrl:1
	v_fmac_f32_dpp v31, v15, v119 row_shr:1 row_mask:0xf bank_mask:0xf bound_ctrl:1
	v_fmac_f32_dpp v30, v14, v138 row_shr:2 row_mask:0xf bank_mask:0xf bound_ctrl:1
	v_fmac_f32_dpp v31, v15, v139 row_shr:2 row_mask:0xf bank_mask:0xf bound_ctrl:1
	s_cbranch_vccnz .LBB0_1017
	ds_read_b128 v[12:15], v152 offset:16
	ds_read_b128 v[56:59], v153 offset:16
	s_waitcnt lgkmcnt(0)
	v_cndmask_b32_e64 v56, v12, v56, s[8:9]
	v_mul_f32_e32 v56, v161, v56
	v_fmac_f32_e32 v56, v157, v12
	v_cndmask_b32_e64 v12, v14, v58, s[8:9]
	v_mul_f32_e32 v12, v162, v12
	v_fmac_f32_e32 v12, v158, v14
	v_cndmask_b32_e64 v57, v13, v57, s[8:9]
	v_add_f32_e32 v30, v30, v12
	v_cndmask_b32_e64 v12, v15, v59, s[8:9]
	v_mul_f32_e32 v57, v163, v57
	v_mul_f32_e32 v12, v160, v12
	v_fmac_f32_e32 v57, v159, v13
	v_fmac_f32_e32 v12, v156, v15
	v_add_f32_e32 v28, v28, v56
	v_add_f32_e32 v29, v29, v57
	v_add_f32_e32 v31, v31, v12
